# epilogue de-serialisation: P3 epilogue store ladder (45 redundant vmcnt(0) lgkmcnt(0) -> s_nop), P8 fused-norm returning atomics no longer waited one by one, P7 rowsq loads hoisted to the tile head
# speedup vs baseline: 1.0035x; 1.0030x over previous
; __device__ __forceinline__ float sigmoidf_(float x) { return __builtin_amdgcn_rcpf(1.0f + __expf(-x)); }
;     __device__ __forceinline__ void operator()(const f32x4 (&acc)[2][2][4][2], const Unit& u, int wr, int wc, int fr, int fq) const {
;     ...
;                     const int row = row0 + ai * 128 + m * 16;
;                     f32x4 v0 = acc[ai][bj][m][0], v1 = acc[ai][bj][m][1];
;                     if (mode == 0) { v0 = v0 * s0; v1 = v1 * s1; }
;                     else if (mode == 1) {
; #pragma unroll
;                         for (int j = 0; j < 4; ++j) { v0[j] = sigmoidf_(v0[j] + s0[j]); v1[j] = sigmoidf_(v1[j] + s1[j]); } }
;                     else {
;                         v0 = v0 + s0; v1 = v1 + s1;
; #pragma unroll
;                         for (int j = 0; j < 4; ++j) {
;                             v0[j] = __expf(-0.60653066f * sigmoidf_(v0[j])); v1[j] = __expf(-0.60653066f * sigmoidf_(v1[j])); }
;                     }
.LBB0_400:
	s_cmp_lg_u32 s21, 1
	s_cbranch_scc0 .LBB0_402
	s_nop 0
	v_pk_add_f32 v[138:139], v[134:135], v[102:103]
	v_pk_add_f32 v[136:137], v[132:133], v[100:101]
	v_pk_add_f32 v[140:141], v[128:129], v[96:97]
	v_pk_add_f32 v[142:143], v[130:131], v[98:99]
	v_mul_f32_e32 v136, 0xbfb8aa3b, v136
	v_mul_f32_e32 v140, 0xbfb8aa3b, v140
	v_mul_f32_e32 v137, 0xbfb8aa3b, v137
	v_mul_f32_e32 v141, 0xbfb8aa3b, v141
	v_mul_f32_e32 v138, 0xbfb8aa3b, v138
	v_mul_f32_e32 v142, 0xbfb8aa3b, v142
	v_mul_f32_e32 v139, 0xbfb8aa3b, v139
	v_mul_f32_e32 v143, 0xbfb8aa3b, v143
	v_exp_f32_e32 v136, v136
	v_exp_f32_e32 v140, v140
	v_exp_f32_e32 v137, v137
	v_exp_f32_e32 v141, v141
	v_exp_f32_e32 v138, v138
	v_exp_f32_e32 v142, v142
	v_exp_f32_e32 v139, v139
	v_exp_f32_e32 v143, v143
	v_add_f32_e32 v136, 1.0, v136
	v_add_f32_e32 v140, 1.0, v140
	v_add_f32_e32 v137, 1.0, v137
	v_add_f32_e32 v141, 1.0, v141
	v_add_f32_e32 v138, 1.0, v138
	v_add_f32_e32 v142, 1.0, v142
	v_add_f32_e32 v139, 1.0, v139
	v_add_f32_e32 v143, 1.0, v143
	v_rcp_f32_e32 v136, v136
	v_rcp_f32_e32 v140, v140
	v_rcp_f32_e32 v137, v137
	v_rcp_f32_e32 v141, v141
	v_rcp_f32_e32 v138, v138
	v_rcp_f32_e32 v142, v142
	v_rcp_f32_e32 v139, v139
	v_rcp_f32_e32 v143, v143
	v_mul_f32_e32 v136, 0xbf1b4598, v136
	v_mul_f32_e32 v140, 0xbf1b4598, v140
	v_mul_f32_e32 v137, 0xbf1b4598, v137
	v_mul_f32_e32 v141, 0xbf1b4598, v141
	v_mul_f32_e32 v138, 0xbf1b4598, v138
	v_mul_f32_e32 v142, 0xbf1b4598, v142
	v_mul_f32_e32 v139, 0xbf1b4598, v139
	v_mul_f32_e32 v143, 0xbf1b4598, v143
	v_mul_f32_e32 v136, 0x3fb8aa3b, v136
	v_mul_f32_e32 v140, 0x3fb8aa3b, v140
	v_mul_f32_e32 v137, 0x3fb8aa3b, v137
	v_mul_f32_e32 v141, 0x3fb8aa3b, v141
	v_mul_f32_e32 v138, 0x3fb8aa3b, v138
	v_mul_f32_e32 v142, 0x3fb8aa3b, v142
	v_mul_f32_e32 v139, 0x3fb8aa3b, v139
	v_mul_f32_e32 v143, 0x3fb8aa3b, v143
	v_exp_f32_e32 v136, v136
	v_exp_f32_e32 v140, v140
	v_exp_f32_e32 v137, v137
	v_exp_f32_e32 v141, v141
	v_exp_f32_e32 v138, v138
	v_exp_f32_e32 v142, v142
	v_exp_f32_e32 v139, v139
	v_exp_f32_e32 v143, v143
	s_mov_b64 s[4:5], 0
.LBB0_402:
	s_andn2_b64 vcc, exec, s[4:5]
	s_cbranch_vccnz .LBB0_404
	s_nop 0
	v_add_f32_e32 v137, v128, v96
	v_mul_f32_e32 v137, 0xbfb8aa3b, v137
	v_add_f32_e32 v138, v133, v101
	v_add_f32_e32 v139, v129, v97
	v_exp_f32_e32 v137, v137
	v_mul_f32_e32 v138, 0xbfb8aa3b, v138
	v_mul_f32_e32 v139, 0xbfb8aa3b, v139
	v_exp_f32_e32 v138, v138
	v_exp_f32_e32 v139, v139
	v_add_f32_e32 v137, 1.0, v137
	v_rcp_f32_e32 v140, v137
	v_add_f32_e32 v137, 1.0, v138
	v_add_f32_e32 v138, 1.0, v139
	v_add_f32_e32 v139, v134, v102
	v_add_f32_e32 v141, v130, v98
	v_mul_f32_e32 v139, 0xbfb8aa3b, v139
	v_mul_f32_e32 v141, 0xbfb8aa3b, v141
	v_exp_f32_e32 v139, v139
	v_exp_f32_e32 v142, v141
	v_rcp_f32_e32 v141, v138
	v_add_f32_e32 v136, v132, v100
	v_add_f32_e32 v138, 1.0, v139
	v_add_f32_e32 v139, 1.0, v142
	v_add_f32_e32 v142, v135, v103
	v_mul_f32_e32 v142, 0xbfb8aa3b, v142
	v_exp_f32_e32 v143, v142
	v_add_f32_e32 v142, v131, v99
	v_mul_f32_e32 v136, 0xbfb8aa3b, v136
	v_mul_f32_e32 v142, 0xbfb8aa3b, v142
	v_exp_f32_e32 v136, v136
	v_exp_f32_e32 v144, v142
	v_rcp_f32_e32 v142, v139
	v_add_f32_e32 v139, 1.0, v143
	v_add_f32_e32 v136, 1.0, v136
	v_add_f32_e32 v143, 1.0, v144
	v_rcp_f32_e32 v136, v136
	v_rcp_f32_e32 v137, v137
	v_rcp_f32_e32 v138, v138
	v_rcp_f32_e32 v139, v139
	v_rcp_f32_e32 v143, v143

;     __device__ __forceinline__ void operator()(const f32x4 (&acc)[2][2][4][2], const Unit& u, int wr, int wc, int fr, int fq) const {
;     ...
;                     const int row = row0 + ai * 128 + m * 16;
;                     f32x4 v0 = acc[ai][bj][m][0], v1 = acc[ai][bj][m][1];
;                     if (mode == 0) { v0 = v0 * s0; v1 = v1 * s1; }
.LBB0_410:
	s_nop 0
	v_pk_mul_f32 v[138:139], v[134:135], v[102:103]
	v_pk_mul_f32 v[136:137], v[132:133], v[100:101]
	v_pk_mul_f32 v[142:143], v[130:131], v[98:99]
	v_pk_mul_f32 v[140:141], v[128:129], v[96:97]

; __device__ __forceinline__ float sigmoidf_(float x) { return __builtin_amdgcn_rcpf(1.0f + __expf(-x)); }
;     __device__ __forceinline__ void operator()(const f32x4 (&acc)[2][2][4][2], const Unit& u, int wr, int wc, int fr, int fq) const {
;     ...
;                     const int row = row0 + ai * 128 + m * 16;
;                     f32x4 v0 = acc[ai][bj][m][0], v1 = acc[ai][bj][m][1];
;                     if (mode == 0) { v0 = v0 * s0; v1 = v1 * s1; }
;                     else if (mode == 1) {
; #pragma unroll
;                         for (int j = 0; j < 4; ++j) { v0[j] = sigmoidf_(v0[j] + s0[j]); v1[j] = sigmoidf_(v1[j] + s1[j]); } }
;                     else {
;                         v0 = v0 + s0; v1 = v1 + s1;
; #pragma unroll
;                         for (int j = 0; j < 4; ++j) {
;                             v0[j] = __expf(-0.60653066f * sigmoidf_(v0[j])); v1[j] = __expf(-0.60653066f * sigmoidf_(v1[j])); }
;                     }
.LBB0_414:
	s_cmp_lg_u32 s21, 1
	s_cbranch_scc0 .LBB0_416
	s_nop 0
	v_pk_add_f32 v[130:131], v[126:127], v[102:103]
	v_pk_add_f32 v[128:129], v[124:125], v[100:101]
	v_pk_add_f32 v[132:133], v[120:121], v[96:97]
	v_pk_add_f32 v[134:135], v[122:123], v[98:99]
	v_mul_f32_e32 v128, 0xbfb8aa3b, v128
	v_mul_f32_e32 v132, 0xbfb8aa3b, v132
	v_mul_f32_e32 v129, 0xbfb8aa3b, v129
	v_mul_f32_e32 v133, 0xbfb8aa3b, v133
	v_mul_f32_e32 v130, 0xbfb8aa3b, v130
	v_mul_f32_e32 v134, 0xbfb8aa3b, v134
	v_mul_f32_e32 v131, 0xbfb8aa3b, v131
	v_mul_f32_e32 v135, 0xbfb8aa3b, v135
	v_exp_f32_e32 v128, v128
	v_exp_f32_e32 v132, v132
	v_exp_f32_e32 v129, v129
	v_exp_f32_e32 v133, v133
	v_exp_f32_e32 v130, v130
	v_exp_f32_e32 v134, v134
	v_exp_f32_e32 v131, v131
	v_exp_f32_e32 v135, v135
	v_add_f32_e32 v128, 1.0, v128
	v_add_f32_e32 v132, 1.0, v132
	v_add_f32_e32 v129, 1.0, v129
	v_add_f32_e32 v133, 1.0, v133
	v_add_f32_e32 v130, 1.0, v130
	v_add_f32_e32 v134, 1.0, v134
	v_add_f32_e32 v131, 1.0, v131
	v_add_f32_e32 v135, 1.0, v135
	v_rcp_f32_e32 v128, v128
	v_rcp_f32_e32 v132, v132
	v_rcp_f32_e32 v129, v129
	v_rcp_f32_e32 v133, v133
	v_rcp_f32_e32 v130, v130
	v_rcp_f32_e32 v134, v134
	v_rcp_f32_e32 v131, v131
	v_rcp_f32_e32 v135, v135
	v_mul_f32_e32 v128, 0xbf1b4598, v128
	v_mul_f32_e32 v132, 0xbf1b4598, v132
	v_mul_f32_e32 v129, 0xbf1b4598, v129
	v_mul_f32_e32 v133, 0xbf1b4598, v133
	v_mul_f32_e32 v130, 0xbf1b4598, v130
	v_mul_f32_e32 v134, 0xbf1b4598, v134
	v_mul_f32_e32 v131, 0xbf1b4598, v131
	v_mul_f32_e32 v135, 0xbf1b4598, v135
	v_mul_f32_e32 v128, 0x3fb8aa3b, v128
	v_mul_f32_e32 v132, 0x3fb8aa3b, v132
	v_mul_f32_e32 v129, 0x3fb8aa3b, v129
	v_mul_f32_e32 v133, 0x3fb8aa3b, v133
	v_mul_f32_e32 v130, 0x3fb8aa3b, v130
	v_mul_f32_e32 v134, 0x3fb8aa3b, v134
	v_mul_f32_e32 v131, 0x3fb8aa3b, v131
	v_mul_f32_e32 v135, 0x3fb8aa3b, v135
	v_exp_f32_e32 v128, v128
	v_exp_f32_e32 v132, v132
	v_exp_f32_e32 v129, v129
	v_exp_f32_e32 v133, v133
	v_exp_f32_e32 v130, v130
	v_exp_f32_e32 v134, v134
	v_exp_f32_e32 v131, v131
	v_exp_f32_e32 v135, v135
	s_mov_b64 s[4:5], 0
.LBB0_416:
	s_andn2_b64 vcc, exec, s[4:5]
	s_cbranch_vccnz .LBB0_418
	s_nop 0
	v_add_f32_e32 v129, v120, v96
	v_mul_f32_e32 v129, 0xbfb8aa3b, v129
	v_add_f32_e32 v130, v125, v101
	v_add_f32_e32 v131, v121, v97
	v_exp_f32_e32 v129, v129
	v_mul_f32_e32 v130, 0xbfb8aa3b, v130
	v_mul_f32_e32 v131, 0xbfb8aa3b, v131
	v_exp_f32_e32 v130, v130
	v_exp_f32_e32 v131, v131
	v_add_f32_e32 v129, 1.0, v129
	v_rcp_f32_e32 v132, v129
	v_add_f32_e32 v129, 1.0, v130
	v_add_f32_e32 v130, 1.0, v131
	v_add_f32_e32 v131, v126, v102
	v_add_f32_e32 v133, v122, v98
	v_mul_f32_e32 v131, 0xbfb8aa3b, v131
	v_mul_f32_e32 v133, 0xbfb8aa3b, v133
	v_exp_f32_e32 v131, v131
	v_exp_f32_e32 v134, v133
	v_rcp_f32_e32 v133, v130
	v_add_f32_e32 v128, v124, v100
	v_add_f32_e32 v130, 1.0, v131
	v_add_f32_e32 v131, 1.0, v134
	v_add_f32_e32 v134, v127, v103
	v_mul_f32_e32 v134, 0xbfb8aa3b, v134
	v_exp_f32_e32 v135, v134
	v_add_f32_e32 v134, v123, v99
	v_mul_f32_e32 v128, 0xbfb8aa3b, v128
	v_mul_f32_e32 v134, 0xbfb8aa3b, v134
	v_exp_f32_e32 v128, v128
	v_exp_f32_e32 v136, v134
	v_rcp_f32_e32 v134, v131
	v_add_f32_e32 v131, 1.0, v135
	v_add_f32_e32 v128, 1.0, v128
	v_add_f32_e32 v135, 1.0, v136
	v_rcp_f32_e32 v128, v128
	v_rcp_f32_e32 v129, v129
	v_rcp_f32_e32 v130, v130
	v_rcp_f32_e32 v131, v131
	v_rcp_f32_e32 v135, v135

; __device__ __forceinline__ float sigmoidf_(float x) { return __builtin_amdgcn_rcpf(1.0f + __expf(-x)); }
;     __device__ __forceinline__ void operator()(const f32x4 (&acc)[2][2][4][2], const Unit& u, int wr, int wc, int fr, int fq) const {
;     ...
;                     const int row = row0 + ai * 128 + m * 16;
;                     f32x4 v0 = acc[ai][bj][m][0], v1 = acc[ai][bj][m][1];
;                     if (mode == 0) { v0 = v0 * s0; v1 = v1 * s1; }
;                     else if (mode == 1) {
; #pragma unroll
;                         for (int j = 0; j < 4; ++j) { v0[j] = sigmoidf_(v0[j] + s0[j]); v1[j] = sigmoidf_(v1[j] + s1[j]); } }
;                     else {
;                         v0 = v0 + s0; v1 = v1 + s1;
; #pragma unroll
;                         for (int j = 0; j < 4; ++j) {
;                             v0[j] = __expf(-0.60653066f * sigmoidf_(v0[j])); v1[j] = __expf(-0.60653066f * sigmoidf_(v1[j])); }
;                     }
.LBB0_422:
	s_cmp_lg_u32 s21, 1
	s_cbranch_scc0 .LBB0_424
	s_nop 0
	v_pk_add_f32 v[122:123], v[118:119], v[102:103]
	v_pk_add_f32 v[120:121], v[116:117], v[100:101]
	v_pk_add_f32 v[124:125], v[112:113], v[96:97]
	v_pk_add_f32 v[126:127], v[114:115], v[98:99]
	v_mul_f32_e32 v120, 0xbfb8aa3b, v120
	v_mul_f32_e32 v124, 0xbfb8aa3b, v124
	v_mul_f32_e32 v121, 0xbfb8aa3b, v121
	v_mul_f32_e32 v125, 0xbfb8aa3b, v125
	v_mul_f32_e32 v122, 0xbfb8aa3b, v122
	v_mul_f32_e32 v126, 0xbfb8aa3b, v126
	v_mul_f32_e32 v123, 0xbfb8aa3b, v123
	v_mul_f32_e32 v127, 0xbfb8aa3b, v127
	v_exp_f32_e32 v120, v120
	v_exp_f32_e32 v124, v124
	v_exp_f32_e32 v121, v121
	v_exp_f32_e32 v125, v125
	v_exp_f32_e32 v122, v122
	v_exp_f32_e32 v126, v126
	v_exp_f32_e32 v123, v123
	v_exp_f32_e32 v127, v127
	v_add_f32_e32 v120, 1.0, v120
	v_add_f32_e32 v124, 1.0, v124
	v_add_f32_e32 v121, 1.0, v121
	v_add_f32_e32 v125, 1.0, v125
	v_add_f32_e32 v122, 1.0, v122
	v_add_f32_e32 v126, 1.0, v126
	v_add_f32_e32 v123, 1.0, v123
	v_add_f32_e32 v127, 1.0, v127
	v_rcp_f32_e32 v120, v120
	v_rcp_f32_e32 v124, v124
	v_rcp_f32_e32 v121, v121
	v_rcp_f32_e32 v125, v125
	v_rcp_f32_e32 v122, v122
	v_rcp_f32_e32 v126, v126
	v_rcp_f32_e32 v123, v123
	v_rcp_f32_e32 v127, v127
	v_mul_f32_e32 v120, 0xbf1b4598, v120
	v_mul_f32_e32 v124, 0xbf1b4598, v124
	v_mul_f32_e32 v121, 0xbf1b4598, v121
	v_mul_f32_e32 v125, 0xbf1b4598, v125
	v_mul_f32_e32 v122, 0xbf1b4598, v122
	v_mul_f32_e32 v126, 0xbf1b4598, v126
	v_mul_f32_e32 v123, 0xbf1b4598, v123
	v_mul_f32_e32 v127, 0xbf1b4598, v127
	v_mul_f32_e32 v120, 0x3fb8aa3b, v120
	v_mul_f32_e32 v124, 0x3fb8aa3b, v124
	v_mul_f32_e32 v121, 0x3fb8aa3b, v121
	v_mul_f32_e32 v125, 0x3fb8aa3b, v125
	v_mul_f32_e32 v122, 0x3fb8aa3b, v122
	v_mul_f32_e32 v126, 0x3fb8aa3b, v126
	v_mul_f32_e32 v123, 0x3fb8aa3b, v123
	v_mul_f32_e32 v127, 0x3fb8aa3b, v127
	v_exp_f32_e32 v120, v120
	v_exp_f32_e32 v124, v124
	v_exp_f32_e32 v121, v121
	v_exp_f32_e32 v125, v125
	v_exp_f32_e32 v122, v122
	v_exp_f32_e32 v126, v126
	v_exp_f32_e32 v123, v123
	v_exp_f32_e32 v127, v127
	s_mov_b64 s[4:5], 0
.LBB0_424:
	s_andn2_b64 vcc, exec, s[4:5]
	s_cbranch_vccnz .LBB0_426
	s_nop 0
	v_add_f32_e32 v121, v112, v96
	v_mul_f32_e32 v121, 0xbfb8aa3b, v121
	v_add_f32_e32 v122, v117, v101
	v_add_f32_e32 v123, v113, v97
	v_exp_f32_e32 v121, v121
	v_mul_f32_e32 v122, 0xbfb8aa3b, v122
	v_mul_f32_e32 v123, 0xbfb8aa3b, v123
	v_exp_f32_e32 v122, v122
	v_exp_f32_e32 v123, v123
	v_add_f32_e32 v121, 1.0, v121
	v_rcp_f32_e32 v124, v121
	v_add_f32_e32 v121, 1.0, v122
	v_add_f32_e32 v122, 1.0, v123
	v_add_f32_e32 v123, v118, v102
	v_add_f32_e32 v125, v114, v98
	v_mul_f32_e32 v123, 0xbfb8aa3b, v123
	v_mul_f32_e32 v125, 0xbfb8aa3b, v125
	v_exp_f32_e32 v123, v123
	v_exp_f32_e32 v126, v125
	v_rcp_f32_e32 v125, v122
	v_add_f32_e32 v120, v116, v100
	v_add_f32_e32 v122, 1.0, v123
	v_add_f32_e32 v123, 1.0, v126
	v_add_f32_e32 v126, v119, v103
	v_mul_f32_e32 v126, 0xbfb8aa3b, v126
	v_exp_f32_e32 v127, v126
	v_add_f32_e32 v126, v115, v99
	v_mul_f32_e32 v120, 0xbfb8aa3b, v120
	v_mul_f32_e32 v126, 0xbfb8aa3b, v126
	v_exp_f32_e32 v120, v120
	v_exp_f32_e32 v128, v126
	v_rcp_f32_e32 v126, v123
	v_add_f32_e32 v123, 1.0, v127
	v_add_f32_e32 v120, 1.0, v120
	v_add_f32_e32 v127, 1.0, v128
	v_rcp_f32_e32 v120, v120
	v_rcp_f32_e32 v121, v121
	v_rcp_f32_e32 v122, v122
	v_rcp_f32_e32 v123, v123
	v_rcp_f32_e32 v127, v127

; __device__ __forceinline__ float sigmoidf_(float x) { return __builtin_amdgcn_rcpf(1.0f + __expf(-x)); }
;     __device__ __forceinline__ void operator()(const f32x4 (&acc)[2][2][4][2], const Unit& u, int wr, int wc, int fr, int fq) const {
;     ...
;                     const int row = row0 + ai * 128 + m * 16;
;                     f32x4 v0 = acc[ai][bj][m][0], v1 = acc[ai][bj][m][1];
;                     if (mode == 0) { v0 = v0 * s0; v1 = v1 * s1; }
;                     else if (mode == 1) {
; #pragma unroll
;                         for (int j = 0; j < 4; ++j) { v0[j] = sigmoidf_(v0[j] + s0[j]); v1[j] = sigmoidf_(v1[j] + s1[j]); } }
;                     else {
;                         v0 = v0 + s0; v1 = v1 + s1;
; #pragma unroll
;                         for (int j = 0; j < 4; ++j) {
;                             v0[j] = __expf(-0.60653066f * sigmoidf_(v0[j])); v1[j] = __expf(-0.60653066f * sigmoidf_(v1[j])); }
;                     }
.LBB0_430:
	s_cmp_lg_u32 s21, 1
	s_cbranch_scc0 .LBB0_432
	s_nop 0
	v_pk_add_f32 v[114:115], v[110:111], v[102:103]
	v_pk_add_f32 v[112:113], v[108:109], v[100:101]
	v_pk_add_f32 v[116:117], v[104:105], v[96:97]
	v_pk_add_f32 v[118:119], v[106:107], v[98:99]
	v_mul_f32_e32 v112, 0xbfb8aa3b, v112
	v_mul_f32_e32 v116, 0xbfb8aa3b, v116
	v_mul_f32_e32 v113, 0xbfb8aa3b, v113
	v_mul_f32_e32 v117, 0xbfb8aa3b, v117
	v_mul_f32_e32 v114, 0xbfb8aa3b, v114
	v_mul_f32_e32 v118, 0xbfb8aa3b, v118
	v_mul_f32_e32 v115, 0xbfb8aa3b, v115
	v_mul_f32_e32 v119, 0xbfb8aa3b, v119
	v_exp_f32_e32 v112, v112
	v_exp_f32_e32 v116, v116
	v_exp_f32_e32 v113, v113
	v_exp_f32_e32 v117, v117
	v_exp_f32_e32 v114, v114
	v_exp_f32_e32 v118, v118
	v_exp_f32_e32 v115, v115
	v_exp_f32_e32 v119, v119
	v_add_f32_e32 v112, 1.0, v112
	v_add_f32_e32 v116, 1.0, v116
	v_add_f32_e32 v113, 1.0, v113
	v_add_f32_e32 v117, 1.0, v117
	v_add_f32_e32 v114, 1.0, v114
	v_add_f32_e32 v118, 1.0, v118
	v_add_f32_e32 v115, 1.0, v115
	v_add_f32_e32 v119, 1.0, v119
	v_rcp_f32_e32 v112, v112
	v_rcp_f32_e32 v116, v116
	v_rcp_f32_e32 v113, v113
	v_rcp_f32_e32 v117, v117
	v_rcp_f32_e32 v114, v114
	v_rcp_f32_e32 v118, v118
	v_rcp_f32_e32 v115, v115
	v_rcp_f32_e32 v119, v119
	v_mul_f32_e32 v112, 0xbf1b4598, v112
	v_mul_f32_e32 v116, 0xbf1b4598, v116
	v_mul_f32_e32 v113, 0xbf1b4598, v113
	v_mul_f32_e32 v117, 0xbf1b4598, v117
	v_mul_f32_e32 v114, 0xbf1b4598, v114
	v_mul_f32_e32 v118, 0xbf1b4598, v118
	v_mul_f32_e32 v115, 0xbf1b4598, v115
	v_mul_f32_e32 v119, 0xbf1b4598, v119
	v_mul_f32_e32 v112, 0x3fb8aa3b, v112
	v_mul_f32_e32 v116, 0x3fb8aa3b, v116
	v_mul_f32_e32 v113, 0x3fb8aa3b, v113
	v_mul_f32_e32 v117, 0x3fb8aa3b, v117
	v_mul_f32_e32 v114, 0x3fb8aa3b, v114
	v_mul_f32_e32 v118, 0x3fb8aa3b, v118
	v_mul_f32_e32 v115, 0x3fb8aa3b, v115
	v_mul_f32_e32 v119, 0x3fb8aa3b, v119
	v_exp_f32_e32 v112, v112
	v_exp_f32_e32 v116, v116
	v_exp_f32_e32 v113, v113
	v_exp_f32_e32 v117, v117
	v_exp_f32_e32 v114, v114
	v_exp_f32_e32 v118, v118
	v_exp_f32_e32 v115, v115
	v_exp_f32_e32 v119, v119
	s_mov_b64 s[4:5], 0
.LBB0_432:
	s_andn2_b64 vcc, exec, s[4:5]
	s_cbranch_vccnz .LBB0_434
	s_nop 0
	v_add_f32_e32 v113, v104, v96
	v_mul_f32_e32 v113, 0xbfb8aa3b, v113
	v_add_f32_e32 v114, v109, v101
	v_add_f32_e32 v115, v105, v97
	v_exp_f32_e32 v113, v113
	v_mul_f32_e32 v114, 0xbfb8aa3b, v114
	v_mul_f32_e32 v115, 0xbfb8aa3b, v115
	v_exp_f32_e32 v114, v114
	v_exp_f32_e32 v115, v115
	v_add_f32_e32 v113, 1.0, v113
	v_rcp_f32_e32 v116, v113
	v_add_f32_e32 v113, 1.0, v114
	v_add_f32_e32 v114, 1.0, v115
	v_add_f32_e32 v115, v110, v102
	v_add_f32_e32 v117, v106, v98
	v_mul_f32_e32 v115, 0xbfb8aa3b, v115
	v_mul_f32_e32 v117, 0xbfb8aa3b, v117
	v_exp_f32_e32 v115, v115
	v_exp_f32_e32 v118, v117
	v_rcp_f32_e32 v117, v114
	v_add_f32_e32 v112, v108, v100
	v_add_f32_e32 v114, 1.0, v115
	v_add_f32_e32 v115, 1.0, v118
	v_add_f32_e32 v118, v111, v103
	v_mul_f32_e32 v118, 0xbfb8aa3b, v118
	v_exp_f32_e32 v119, v118
	v_add_f32_e32 v118, v107, v99
	v_mul_f32_e32 v112, 0xbfb8aa3b, v112
	v_mul_f32_e32 v118, 0xbfb8aa3b, v118
	v_exp_f32_e32 v112, v112
	v_exp_f32_e32 v120, v118
	v_rcp_f32_e32 v118, v115
	v_add_f32_e32 v115, 1.0, v119
	v_add_f32_e32 v112, 1.0, v112
	v_add_f32_e32 v119, 1.0, v120
	v_rcp_f32_e32 v112, v112
	v_rcp_f32_e32 v113, v113
	v_rcp_f32_e32 v114, v114
	v_rcp_f32_e32 v115, v115
	v_rcp_f32_e32 v119, v119

; __device__ __forceinline__ float sigmoidf_(float x) { return __builtin_amdgcn_rcpf(1.0f + __expf(-x)); }
;     __device__ __forceinline__ void operator()(const f32x4 (&acc)[2][2][4][2], const Unit& u, int wr, int wc, int fr, int fq) const {
;     ...
;                     const int row = row0 + ai * 128 + m * 16;
;                     f32x4 v0 = acc[ai][bj][m][0], v1 = acc[ai][bj][m][1];
;                     if (mode == 0) { v0 = v0 * s0; v1 = v1 * s1; }
;                     else if (mode == 1) {
; #pragma unroll
;                         for (int j = 0; j < 4; ++j) { v0[j] = sigmoidf_(v0[j] + s0[j]); v1[j] = sigmoidf_(v1[j] + s1[j]); } }
;                     else {
;                         v0 = v0 + s0; v1 = v1 + s1;
; #pragma unroll
;                         for (int j = 0; j < 4; ++j) {
;                             v0[j] = __expf(-0.60653066f * sigmoidf_(v0[j])); v1[j] = __expf(-0.60653066f * sigmoidf_(v1[j])); }
;                     }
.LBB0_438:
	s_cmp_lg_u32 s21, 1
	s_cbranch_scc0 .LBB0_440
	s_nop 0
	v_pk_add_f32 v[106:107], v[94:95], v[102:103]
	v_pk_add_f32 v[104:105], v[92:93], v[100:101]
	v_pk_add_f32 v[108:109], v[88:89], v[96:97]
	v_pk_add_f32 v[110:111], v[90:91], v[98:99]
	v_mul_f32_e32 v104, 0xbfb8aa3b, v104
	v_mul_f32_e32 v108, 0xbfb8aa3b, v108
	v_mul_f32_e32 v105, 0xbfb8aa3b, v105
	v_mul_f32_e32 v109, 0xbfb8aa3b, v109
	v_mul_f32_e32 v106, 0xbfb8aa3b, v106
	v_mul_f32_e32 v110, 0xbfb8aa3b, v110
	v_mul_f32_e32 v107, 0xbfb8aa3b, v107
	v_mul_f32_e32 v111, 0xbfb8aa3b, v111
	v_exp_f32_e32 v104, v104
	v_exp_f32_e32 v108, v108
	v_exp_f32_e32 v105, v105
	v_exp_f32_e32 v109, v109
	v_exp_f32_e32 v106, v106
	v_exp_f32_e32 v110, v110
	v_exp_f32_e32 v107, v107
	v_exp_f32_e32 v111, v111
	v_add_f32_e32 v104, 1.0, v104
	v_add_f32_e32 v108, 1.0, v108
	v_add_f32_e32 v105, 1.0, v105
	v_add_f32_e32 v109, 1.0, v109
	v_add_f32_e32 v106, 1.0, v106
	v_add_f32_e32 v110, 1.0, v110
	v_add_f32_e32 v107, 1.0, v107
	v_add_f32_e32 v111, 1.0, v111
	v_rcp_f32_e32 v104, v104
	v_rcp_f32_e32 v108, v108
	v_rcp_f32_e32 v105, v105
	v_rcp_f32_e32 v109, v109
	v_rcp_f32_e32 v106, v106
	v_rcp_f32_e32 v110, v110
	v_rcp_f32_e32 v107, v107
	v_rcp_f32_e32 v111, v111
	v_mul_f32_e32 v104, 0xbf1b4598, v104
	v_mul_f32_e32 v108, 0xbf1b4598, v108
	v_mul_f32_e32 v105, 0xbf1b4598, v105
	v_mul_f32_e32 v109, 0xbf1b4598, v109
	v_mul_f32_e32 v106, 0xbf1b4598, v106
	v_mul_f32_e32 v110, 0xbf1b4598, v110
	v_mul_f32_e32 v107, 0xbf1b4598, v107
	v_mul_f32_e32 v111, 0xbf1b4598, v111
	v_mul_f32_e32 v104, 0x3fb8aa3b, v104
	v_mul_f32_e32 v108, 0x3fb8aa3b, v108
	v_mul_f32_e32 v105, 0x3fb8aa3b, v105
	v_mul_f32_e32 v109, 0x3fb8aa3b, v109
	v_mul_f32_e32 v106, 0x3fb8aa3b, v106
	v_mul_f32_e32 v110, 0x3fb8aa3b, v110
	v_mul_f32_e32 v107, 0x3fb8aa3b, v107
	v_mul_f32_e32 v111, 0x3fb8aa3b, v111
	v_exp_f32_e32 v104, v104
	v_exp_f32_e32 v108, v108
	v_exp_f32_e32 v105, v105
	v_exp_f32_e32 v109, v109
	v_exp_f32_e32 v106, v106
	v_exp_f32_e32 v110, v110
	v_exp_f32_e32 v107, v107
	v_exp_f32_e32 v111, v111
	s_mov_b64 s[4:5], 0
.LBB0_440:
	s_andn2_b64 vcc, exec, s[4:5]
	s_cbranch_vccnz .LBB0_442
	s_nop 0
	v_add_f32_e32 v105, v88, v96
	v_mul_f32_e32 v105, 0xbfb8aa3b, v105
	v_add_f32_e32 v106, v93, v101
	v_add_f32_e32 v107, v89, v97
	v_exp_f32_e32 v105, v105
	v_mul_f32_e32 v106, 0xbfb8aa3b, v106
	v_mul_f32_e32 v107, 0xbfb8aa3b, v107
	v_exp_f32_e32 v106, v106
	v_exp_f32_e32 v107, v107
	v_add_f32_e32 v105, 1.0, v105
	v_rcp_f32_e32 v108, v105
	v_add_f32_e32 v105, 1.0, v106
	v_add_f32_e32 v106, 1.0, v107
	v_add_f32_e32 v107, v94, v102
	v_add_f32_e32 v109, v90, v98
	v_mul_f32_e32 v107, 0xbfb8aa3b, v107
	v_mul_f32_e32 v109, 0xbfb8aa3b, v109
	v_exp_f32_e32 v107, v107
	v_exp_f32_e32 v110, v109
	v_rcp_f32_e32 v109, v106
	v_add_f32_e32 v104, v92, v100
	v_add_f32_e32 v106, 1.0, v107
	v_add_f32_e32 v107, 1.0, v110
	v_add_f32_e32 v110, v95, v103
	v_mul_f32_e32 v110, 0xbfb8aa3b, v110
	v_exp_f32_e32 v111, v110
	v_add_f32_e32 v110, v91, v99
	v_mul_f32_e32 v104, 0xbfb8aa3b, v104
	v_mul_f32_e32 v110, 0xbfb8aa3b, v110
	v_exp_f32_e32 v104, v104
	v_exp_f32_e32 v112, v110
	v_rcp_f32_e32 v110, v107
	v_add_f32_e32 v107, 1.0, v111
	v_add_f32_e32 v104, 1.0, v104
	v_add_f32_e32 v111, 1.0, v112
	v_rcp_f32_e32 v104, v104
	v_rcp_f32_e32 v105, v105
	v_rcp_f32_e32 v106, v106
	v_rcp_f32_e32 v107, v107
	v_rcp_f32_e32 v111, v111

; __device__ __forceinline__ float sigmoidf_(float x) { return __builtin_amdgcn_rcpf(1.0f + __expf(-x)); }
;     __device__ __forceinline__ void operator()(const f32x4 (&acc)[2][2][4][2], const Unit& u, int wr, int wc, int fr, int fq) const {
;     ...
;                     const int row = row0 + ai * 128 + m * 16;
;                     f32x4 v0 = acc[ai][bj][m][0], v1 = acc[ai][bj][m][1];
;                     if (mode == 0) { v0 = v0 * s0; v1 = v1 * s1; }
;                     else if (mode == 1) {
; #pragma unroll
;                         for (int j = 0; j < 4; ++j) { v0[j] = sigmoidf_(v0[j] + s0[j]); v1[j] = sigmoidf_(v1[j] + s1[j]); } }
;                     else {
;                         v0 = v0 + s0; v1 = v1 + s1;
; #pragma unroll
;                         for (int j = 0; j < 4; ++j) {
;                             v0[j] = __expf(-0.60653066f * sigmoidf_(v0[j])); v1[j] = __expf(-0.60653066f * sigmoidf_(v1[j])); }
;                     }
.LBB0_446:
	s_cmp_lg_u32 s21, 1
	s_cbranch_scc0 .LBB0_448
	s_nop 0
	v_pk_add_f32 v[90:91], v[86:87], v[102:103]
	v_pk_add_f32 v[88:89], v[84:85], v[100:101]
	v_pk_add_f32 v[92:93], v[80:81], v[96:97]
	v_pk_add_f32 v[94:95], v[82:83], v[98:99]
	v_mul_f32_e32 v88, 0xbfb8aa3b, v88
	v_mul_f32_e32 v92, 0xbfb8aa3b, v92
	v_mul_f32_e32 v89, 0xbfb8aa3b, v89
	v_mul_f32_e32 v93, 0xbfb8aa3b, v93
	v_mul_f32_e32 v90, 0xbfb8aa3b, v90
	v_mul_f32_e32 v94, 0xbfb8aa3b, v94
	v_mul_f32_e32 v91, 0xbfb8aa3b, v91
	v_mul_f32_e32 v95, 0xbfb8aa3b, v95
	v_exp_f32_e32 v88, v88
	v_exp_f32_e32 v92, v92
	v_exp_f32_e32 v89, v89
	v_exp_f32_e32 v93, v93
	v_exp_f32_e32 v90, v90
	v_exp_f32_e32 v94, v94
	v_exp_f32_e32 v91, v91
	v_exp_f32_e32 v95, v95
	v_add_f32_e32 v88, 1.0, v88
	v_add_f32_e32 v92, 1.0, v92
	v_add_f32_e32 v89, 1.0, v89
	v_add_f32_e32 v93, 1.0, v93
	v_add_f32_e32 v90, 1.0, v90
	v_add_f32_e32 v94, 1.0, v94
	v_add_f32_e32 v91, 1.0, v91
	v_add_f32_e32 v95, 1.0, v95
	v_rcp_f32_e32 v88, v88
	v_rcp_f32_e32 v92, v92
	v_rcp_f32_e32 v89, v89
	v_rcp_f32_e32 v93, v93
	v_rcp_f32_e32 v90, v90
	v_rcp_f32_e32 v94, v94
	v_rcp_f32_e32 v91, v91
	v_rcp_f32_e32 v95, v95
	v_mul_f32_e32 v88, 0xbf1b4598, v88
	v_mul_f32_e32 v92, 0xbf1b4598, v92
	v_mul_f32_e32 v89, 0xbf1b4598, v89
	v_mul_f32_e32 v93, 0xbf1b4598, v93
	v_mul_f32_e32 v90, 0xbf1b4598, v90
	v_mul_f32_e32 v94, 0xbf1b4598, v94
	v_mul_f32_e32 v91, 0xbf1b4598, v91
	v_mul_f32_e32 v95, 0xbf1b4598, v95
	v_mul_f32_e32 v88, 0x3fb8aa3b, v88
	v_mul_f32_e32 v92, 0x3fb8aa3b, v92
	v_mul_f32_e32 v89, 0x3fb8aa3b, v89
	v_mul_f32_e32 v93, 0x3fb8aa3b, v93
	v_mul_f32_e32 v90, 0x3fb8aa3b, v90
	v_mul_f32_e32 v94, 0x3fb8aa3b, v94
	v_mul_f32_e32 v91, 0x3fb8aa3b, v91
	v_mul_f32_e32 v95, 0x3fb8aa3b, v95
	v_exp_f32_e32 v88, v88
	v_exp_f32_e32 v92, v92
	v_exp_f32_e32 v89, v89
	v_exp_f32_e32 v93, v93
	v_exp_f32_e32 v90, v90
	v_exp_f32_e32 v94, v94
	v_exp_f32_e32 v91, v91
	v_exp_f32_e32 v95, v95
	s_mov_b64 s[4:5], 0
.LBB0_448:
	s_andn2_b64 vcc, exec, s[4:5]
	s_cbranch_vccnz .LBB0_450
	s_nop 0
	v_add_f32_e32 v89, v80, v96
	v_mul_f32_e32 v89, 0xbfb8aa3b, v89
	v_add_f32_e32 v90, v85, v101
	v_add_f32_e32 v91, v81, v97
	v_exp_f32_e32 v89, v89
	v_mul_f32_e32 v90, 0xbfb8aa3b, v90
	v_mul_f32_e32 v91, 0xbfb8aa3b, v91
	v_exp_f32_e32 v90, v90
	v_exp_f32_e32 v91, v91
	v_add_f32_e32 v89, 1.0, v89
	v_rcp_f32_e32 v92, v89
	v_add_f32_e32 v89, 1.0, v90
	v_add_f32_e32 v90, 1.0, v91
	v_add_f32_e32 v91, v86, v102
	v_add_f32_e32 v93, v82, v98
	v_mul_f32_e32 v91, 0xbfb8aa3b, v91
	v_mul_f32_e32 v93, 0xbfb8aa3b, v93
	v_exp_f32_e32 v91, v91
	v_exp_f32_e32 v94, v93
	v_rcp_f32_e32 v93, v90
	v_add_f32_e32 v88, v84, v100
	v_add_f32_e32 v90, 1.0, v91
	v_add_f32_e32 v91, 1.0, v94
	v_add_f32_e32 v94, v87, v103
	v_mul_f32_e32 v94, 0xbfb8aa3b, v94
	v_exp_f32_e32 v95, v94
	v_add_f32_e32 v94, v83, v99
	v_mul_f32_e32 v88, 0xbfb8aa3b, v88
	v_mul_f32_e32 v94, 0xbfb8aa3b, v94
	v_exp_f32_e32 v88, v88
	v_exp_f32_e32 v104, v94
	v_rcp_f32_e32 v94, v91
	v_add_f32_e32 v91, 1.0, v95
	v_add_f32_e32 v88, 1.0, v88
	v_add_f32_e32 v95, 1.0, v104
	v_rcp_f32_e32 v88, v88
	v_rcp_f32_e32 v89, v89
	v_rcp_f32_e32 v90, v90
	v_rcp_f32_e32 v91, v91
	v_rcp_f32_e32 v95, v95

; __device__ __forceinline__ float sigmoidf_(float x) { return __builtin_amdgcn_rcpf(1.0f + __expf(-x)); }
;     __device__ __forceinline__ void operator()(const f32x4 (&acc)[2][2][4][2], const Unit& u, int wr, int wc, int fr, int fq) const {
;     ...
;                     const int row = row0 + ai * 128 + m * 16;
;                     f32x4 v0 = acc[ai][bj][m][0], v1 = acc[ai][bj][m][1];
;                     if (mode == 0) { v0 = v0 * s0; v1 = v1 * s1; }
;                     else if (mode == 1) {
; #pragma unroll
;                         for (int j = 0; j < 4; ++j) { v0[j] = sigmoidf_(v0[j] + s0[j]); v1[j] = sigmoidf_(v1[j] + s1[j]); } }
;                     else {
;                         v0 = v0 + s0; v1 = v1 + s1;
; #pragma unroll
;                         for (int j = 0; j < 4; ++j) {
;                             v0[j] = __expf(-0.60653066f * sigmoidf_(v0[j])); v1[j] = __expf(-0.60653066f * sigmoidf_(v1[j])); }
;                     }
.LBB0_454:
	s_cmp_lg_u32 s21, 1
	s_cbranch_scc0 .LBB0_456
	s_nop 0
	v_pk_add_f32 v[82:83], v[78:79], v[102:103]
	v_pk_add_f32 v[80:81], v[76:77], v[100:101]
	v_pk_add_f32 v[84:85], v[72:73], v[96:97]
	v_pk_add_f32 v[86:87], v[74:75], v[98:99]
	v_mul_f32_e32 v80, 0xbfb8aa3b, v80
	v_mul_f32_e32 v84, 0xbfb8aa3b, v84
	v_mul_f32_e32 v81, 0xbfb8aa3b, v81
	v_mul_f32_e32 v85, 0xbfb8aa3b, v85
	v_mul_f32_e32 v82, 0xbfb8aa3b, v82
	v_mul_f32_e32 v86, 0xbfb8aa3b, v86
	v_mul_f32_e32 v83, 0xbfb8aa3b, v83
	v_mul_f32_e32 v87, 0xbfb8aa3b, v87
	v_exp_f32_e32 v80, v80
	v_exp_f32_e32 v84, v84
	v_exp_f32_e32 v81, v81
	v_exp_f32_e32 v85, v85
	v_exp_f32_e32 v82, v82
	v_exp_f32_e32 v86, v86
	v_exp_f32_e32 v83, v83
	v_exp_f32_e32 v87, v87
	v_add_f32_e32 v80, 1.0, v80
	v_add_f32_e32 v84, 1.0, v84
	v_add_f32_e32 v81, 1.0, v81
	v_add_f32_e32 v85, 1.0, v85
	v_add_f32_e32 v82, 1.0, v82
	v_add_f32_e32 v86, 1.0, v86
	v_add_f32_e32 v83, 1.0, v83
	v_add_f32_e32 v87, 1.0, v87
	v_rcp_f32_e32 v80, v80
	v_rcp_f32_e32 v84, v84
	v_rcp_f32_e32 v81, v81
	v_rcp_f32_e32 v85, v85
	v_rcp_f32_e32 v82, v82
	v_rcp_f32_e32 v86, v86
	v_rcp_f32_e32 v83, v83
	v_rcp_f32_e32 v87, v87
	v_mul_f32_e32 v80, 0xbf1b4598, v80
	v_mul_f32_e32 v84, 0xbf1b4598, v84
	v_mul_f32_e32 v81, 0xbf1b4598, v81
	v_mul_f32_e32 v85, 0xbf1b4598, v85
	v_mul_f32_e32 v82, 0xbf1b4598, v82
	v_mul_f32_e32 v86, 0xbf1b4598, v86
	v_mul_f32_e32 v83, 0xbf1b4598, v83
	v_mul_f32_e32 v87, 0xbf1b4598, v87
	v_mul_f32_e32 v80, 0x3fb8aa3b, v80
	v_mul_f32_e32 v84, 0x3fb8aa3b, v84
	v_mul_f32_e32 v81, 0x3fb8aa3b, v81
	v_mul_f32_e32 v85, 0x3fb8aa3b, v85
	v_mul_f32_e32 v82, 0x3fb8aa3b, v82
	v_mul_f32_e32 v86, 0x3fb8aa3b, v86
	v_mul_f32_e32 v83, 0x3fb8aa3b, v83
	v_mul_f32_e32 v87, 0x3fb8aa3b, v87
	v_exp_f32_e32 v80, v80
	v_exp_f32_e32 v84, v84
	v_exp_f32_e32 v81, v81
	v_exp_f32_e32 v85, v85
	v_exp_f32_e32 v82, v82
	v_exp_f32_e32 v86, v86
	v_exp_f32_e32 v83, v83
	v_exp_f32_e32 v87, v87
	s_mov_b64 s[4:5], 0
.LBB0_456:
	s_andn2_b64 vcc, exec, s[4:5]
	s_cbranch_vccnz .LBB0_458
	s_nop 0
	v_add_f32_e32 v81, v72, v96
	v_mul_f32_e32 v81, 0xbfb8aa3b, v81
	v_add_f32_e32 v82, v77, v101
	v_add_f32_e32 v83, v73, v97
	v_exp_f32_e32 v81, v81
	v_mul_f32_e32 v82, 0xbfb8aa3b, v82
	v_mul_f32_e32 v83, 0xbfb8aa3b, v83
	v_exp_f32_e32 v82, v82
	v_exp_f32_e32 v83, v83
	v_add_f32_e32 v81, 1.0, v81
	v_rcp_f32_e32 v84, v81
	v_add_f32_e32 v81, 1.0, v82
	v_add_f32_e32 v82, 1.0, v83
	v_add_f32_e32 v83, v78, v102
	v_add_f32_e32 v85, v74, v98
	v_mul_f32_e32 v83, 0xbfb8aa3b, v83
	v_mul_f32_e32 v85, 0xbfb8aa3b, v85
	v_exp_f32_e32 v83, v83
	v_exp_f32_e32 v86, v85
	v_rcp_f32_e32 v85, v82
	v_add_f32_e32 v80, v76, v100
	v_add_f32_e32 v82, 1.0, v83
	v_add_f32_e32 v83, 1.0, v86
	v_add_f32_e32 v86, v79, v103
	v_mul_f32_e32 v86, 0xbfb8aa3b, v86
	v_exp_f32_e32 v87, v86
	v_add_f32_e32 v86, v75, v99
	v_mul_f32_e32 v80, 0xbfb8aa3b, v80
	v_mul_f32_e32 v86, 0xbfb8aa3b, v86
	v_exp_f32_e32 v80, v80
	v_exp_f32_e32 v88, v86
	v_rcp_f32_e32 v86, v83
	v_add_f32_e32 v83, 1.0, v87
	v_add_f32_e32 v80, 1.0, v80
	v_add_f32_e32 v87, 1.0, v88
	v_rcp_f32_e32 v80, v80
	v_rcp_f32_e32 v81, v81
	v_rcp_f32_e32 v82, v82
	v_rcp_f32_e32 v83, v83
	v_rcp_f32_e32 v87, v87

; __device__ __forceinline__ float sigmoidf_(float x) { return __builtin_amdgcn_rcpf(1.0f + __expf(-x)); }
;     __device__ __forceinline__ void operator()(const f32x4 (&acc)[2][2][4][2], const Unit& u, int wr, int wc, int fr, int fq) const {
;     ...
;                     const int row = row0 + ai * 128 + m * 16;
;                     f32x4 v0 = acc[ai][bj][m][0], v1 = acc[ai][bj][m][1];
;                     if (mode == 0) { v0 = v0 * s0; v1 = v1 * s1; }
;                     else if (mode == 1) {
; #pragma unroll
;                         for (int j = 0; j < 4; ++j) { v0[j] = sigmoidf_(v0[j] + s0[j]); v1[j] = sigmoidf_(v1[j] + s1[j]); } }
;                     else {
;                         v0 = v0 + s0; v1 = v1 + s1;
; #pragma unroll
;                         for (int j = 0; j < 4; ++j) {
;                             v0[j] = __expf(-0.60653066f * sigmoidf_(v0[j])); v1[j] = __expf(-0.60653066f * sigmoidf_(v1[j])); }
;                     }
.LBB0_462:
	s_cmp_lg_u32 s21, 1
	s_cbranch_scc0 .LBB0_464
	s_nop 0
	v_pk_add_f32 v[74:75], v[70:71], v[30:31]
	v_pk_add_f32 v[72:73], v[68:69], v[28:29]
	v_pk_add_f32 v[76:77], v[64:65], v[24:25]
	v_pk_add_f32 v[78:79], v[66:67], v[26:27]
	v_mul_f32_e32 v72, 0xbfb8aa3b, v72
	v_mul_f32_e32 v76, 0xbfb8aa3b, v76
	v_mul_f32_e32 v73, 0xbfb8aa3b, v73
	v_mul_f32_e32 v77, 0xbfb8aa3b, v77
	v_mul_f32_e32 v74, 0xbfb8aa3b, v74
	v_mul_f32_e32 v78, 0xbfb8aa3b, v78
	v_mul_f32_e32 v75, 0xbfb8aa3b, v75
	v_mul_f32_e32 v79, 0xbfb8aa3b, v79
	v_exp_f32_e32 v72, v72
	v_exp_f32_e32 v76, v76
	v_exp_f32_e32 v73, v73
	v_exp_f32_e32 v77, v77
	v_exp_f32_e32 v74, v74
	v_exp_f32_e32 v78, v78
	v_exp_f32_e32 v75, v75
	v_exp_f32_e32 v79, v79
	v_add_f32_e32 v72, 1.0, v72
	v_add_f32_e32 v76, 1.0, v76
	v_add_f32_e32 v73, 1.0, v73
	v_add_f32_e32 v77, 1.0, v77
	v_add_f32_e32 v74, 1.0, v74
	v_add_f32_e32 v78, 1.0, v78
	v_add_f32_e32 v75, 1.0, v75
	v_add_f32_e32 v79, 1.0, v79
	v_rcp_f32_e32 v72, v72
	v_rcp_f32_e32 v76, v76
	v_rcp_f32_e32 v73, v73
	v_rcp_f32_e32 v77, v77
	v_rcp_f32_e32 v74, v74
	v_rcp_f32_e32 v78, v78
	v_rcp_f32_e32 v75, v75
	v_rcp_f32_e32 v79, v79
	v_mul_f32_e32 v72, 0xbf1b4598, v72
	v_mul_f32_e32 v76, 0xbf1b4598, v76
	v_mul_f32_e32 v73, 0xbf1b4598, v73
	v_mul_f32_e32 v77, 0xbf1b4598, v77
	v_mul_f32_e32 v74, 0xbf1b4598, v74
	v_mul_f32_e32 v78, 0xbf1b4598, v78
	v_mul_f32_e32 v75, 0xbf1b4598, v75
	v_mul_f32_e32 v79, 0xbf1b4598, v79
	v_mul_f32_e32 v72, 0x3fb8aa3b, v72
	v_mul_f32_e32 v76, 0x3fb8aa3b, v76
	v_mul_f32_e32 v73, 0x3fb8aa3b, v73
	v_mul_f32_e32 v77, 0x3fb8aa3b, v77
	v_mul_f32_e32 v74, 0x3fb8aa3b, v74
	v_mul_f32_e32 v78, 0x3fb8aa3b, v78
	v_mul_f32_e32 v75, 0x3fb8aa3b, v75
	v_mul_f32_e32 v79, 0x3fb8aa3b, v79
	v_exp_f32_e32 v72, v72
	v_exp_f32_e32 v76, v76
	v_exp_f32_e32 v73, v73
	v_exp_f32_e32 v77, v77
	v_exp_f32_e32 v74, v74
	v_exp_f32_e32 v78, v78
	v_exp_f32_e32 v75, v75
	v_exp_f32_e32 v79, v79
	s_mov_b64 s[4:5], 0
.LBB0_464:
	s_andn2_b64 vcc, exec, s[4:5]
	s_cbranch_vccnz .LBB0_466
	s_nop 0
	v_add_f32_e32 v73, v64, v24
	v_mul_f32_e32 v73, 0xbfb8aa3b, v73
	v_add_f32_e32 v74, v69, v29
	v_add_f32_e32 v75, v65, v25
	v_exp_f32_e32 v73, v73
	v_mul_f32_e32 v74, 0xbfb8aa3b, v74
	v_mul_f32_e32 v75, 0xbfb8aa3b, v75
	v_exp_f32_e32 v74, v74
	v_exp_f32_e32 v75, v75
	v_add_f32_e32 v73, 1.0, v73
	v_rcp_f32_e32 v76, v73
	v_add_f32_e32 v73, 1.0, v74
	v_add_f32_e32 v74, 1.0, v75
	v_add_f32_e32 v75, v70, v30
	v_add_f32_e32 v77, v66, v26
	v_mul_f32_e32 v75, 0xbfb8aa3b, v75
	v_mul_f32_e32 v77, 0xbfb8aa3b, v77
	v_exp_f32_e32 v75, v75
	v_exp_f32_e32 v78, v77
	v_rcp_f32_e32 v77, v74
	v_add_f32_e32 v72, v68, v28
	v_add_f32_e32 v74, 1.0, v75
	v_add_f32_e32 v75, 1.0, v78
	v_add_f32_e32 v78, v71, v31
	v_mul_f32_e32 v78, 0xbfb8aa3b, v78
	v_exp_f32_e32 v79, v78
	v_add_f32_e32 v78, v67, v27
	v_mul_f32_e32 v72, 0xbfb8aa3b, v72
	v_mul_f32_e32 v78, 0xbfb8aa3b, v78
	v_exp_f32_e32 v72, v72
	v_exp_f32_e32 v80, v78
	v_rcp_f32_e32 v78, v75
	v_add_f32_e32 v75, 1.0, v79
	v_add_f32_e32 v72, 1.0, v72
	v_add_f32_e32 v79, 1.0, v80
	v_rcp_f32_e32 v72, v72
	v_rcp_f32_e32 v73, v73
	v_rcp_f32_e32 v74, v74
	v_rcp_f32_e32 v75, v75
	v_rcp_f32_e32 v79, v79

; __device__ __forceinline__ float sigmoidf_(float x) { return __builtin_amdgcn_rcpf(1.0f + __expf(-x)); }
;     __device__ __forceinline__ void operator()(const f32x4 (&acc)[2][2][4][2], const Unit& u, int wr, int wc, int fr, int fq) const {
;     ...
;                     const int row = row0 + ai * 128 + m * 16;
;                     f32x4 v0 = acc[ai][bj][m][0], v1 = acc[ai][bj][m][1];
;                     if (mode == 0) { v0 = v0 * s0; v1 = v1 * s1; }
;                     else if (mode == 1) {
; #pragma unroll
;                         for (int j = 0; j < 4; ++j) { v0[j] = sigmoidf_(v0[j] + s0[j]); v1[j] = sigmoidf_(v1[j] + s1[j]); } }
;                     else {
;                         v0 = v0 + s0; v1 = v1 + s1;
; #pragma unroll
;                         for (int j = 0; j < 4; ++j) {
;                             v0[j] = __expf(-0.60653066f * sigmoidf_(v0[j])); v1[j] = __expf(-0.60653066f * sigmoidf_(v1[j])); }
;                     }
.LBB0_470:
	s_cmp_lg_u32 s21, 1
	s_cbranch_scc0 .LBB0_472
	s_nop 0
	v_pk_add_f32 v[66:67], v[62:63], v[30:31]
	v_pk_add_f32 v[64:65], v[60:61], v[28:29]
	v_pk_add_f32 v[68:69], v[56:57], v[24:25]
	v_pk_add_f32 v[70:71], v[58:59], v[26:27]
	v_mul_f32_e32 v64, 0xbfb8aa3b, v64
	v_mul_f32_e32 v68, 0xbfb8aa3b, v68
	v_mul_f32_e32 v65, 0xbfb8aa3b, v65
	v_mul_f32_e32 v69, 0xbfb8aa3b, v69
	v_mul_f32_e32 v66, 0xbfb8aa3b, v66
	v_mul_f32_e32 v70, 0xbfb8aa3b, v70
	v_mul_f32_e32 v67, 0xbfb8aa3b, v67
	v_mul_f32_e32 v71, 0xbfb8aa3b, v71
	v_exp_f32_e32 v64, v64
	v_exp_f32_e32 v68, v68
	v_exp_f32_e32 v65, v65
	v_exp_f32_e32 v69, v69
	v_exp_f32_e32 v66, v66
	v_exp_f32_e32 v70, v70
	v_exp_f32_e32 v67, v67
	v_exp_f32_e32 v71, v71
	v_add_f32_e32 v64, 1.0, v64
	v_add_f32_e32 v68, 1.0, v68
	v_add_f32_e32 v65, 1.0, v65
	v_add_f32_e32 v69, 1.0, v69
	v_add_f32_e32 v66, 1.0, v66
	v_add_f32_e32 v70, 1.0, v70
	v_add_f32_e32 v67, 1.0, v67
	v_add_f32_e32 v71, 1.0, v71
	v_rcp_f32_e32 v64, v64
	v_rcp_f32_e32 v68, v68
	v_rcp_f32_e32 v65, v65
	v_rcp_f32_e32 v69, v69
	v_rcp_f32_e32 v66, v66
	v_rcp_f32_e32 v70, v70
	v_rcp_f32_e32 v67, v67
	v_rcp_f32_e32 v71, v71
	v_mul_f32_e32 v64, 0xbf1b4598, v64
	v_mul_f32_e32 v68, 0xbf1b4598, v68
	v_mul_f32_e32 v65, 0xbf1b4598, v65
	v_mul_f32_e32 v69, 0xbf1b4598, v69
	v_mul_f32_e32 v66, 0xbf1b4598, v66
	v_mul_f32_e32 v70, 0xbf1b4598, v70
	v_mul_f32_e32 v67, 0xbf1b4598, v67
	v_mul_f32_e32 v71, 0xbf1b4598, v71
	v_mul_f32_e32 v64, 0x3fb8aa3b, v64
	v_mul_f32_e32 v68, 0x3fb8aa3b, v68
	v_mul_f32_e32 v65, 0x3fb8aa3b, v65
	v_mul_f32_e32 v69, 0x3fb8aa3b, v69
	v_mul_f32_e32 v66, 0x3fb8aa3b, v66
	v_mul_f32_e32 v70, 0x3fb8aa3b, v70
	v_mul_f32_e32 v67, 0x3fb8aa3b, v67
	v_mul_f32_e32 v71, 0x3fb8aa3b, v71
	v_exp_f32_e32 v64, v64
	v_exp_f32_e32 v68, v68
	v_exp_f32_e32 v65, v65
	v_exp_f32_e32 v69, v69
	v_exp_f32_e32 v66, v66
	v_exp_f32_e32 v70, v70
	v_exp_f32_e32 v67, v67
	v_exp_f32_e32 v71, v71
	s_mov_b64 s[4:5], 0
.LBB0_472:
	s_andn2_b64 vcc, exec, s[4:5]
	s_cbranch_vccnz .LBB0_474
	s_nop 0
	v_add_f32_e32 v65, v56, v24
	v_mul_f32_e32 v65, 0xbfb8aa3b, v65
	v_add_f32_e32 v66, v61, v29
	v_add_f32_e32 v67, v57, v25
	v_exp_f32_e32 v65, v65
	v_mul_f32_e32 v66, 0xbfb8aa3b, v66
	v_mul_f32_e32 v67, 0xbfb8aa3b, v67
	v_exp_f32_e32 v66, v66
	v_exp_f32_e32 v67, v67
	v_add_f32_e32 v65, 1.0, v65
	v_rcp_f32_e32 v68, v65
	v_add_f32_e32 v65, 1.0, v66
	v_add_f32_e32 v66, 1.0, v67
	v_add_f32_e32 v67, v62, v30
	v_add_f32_e32 v69, v58, v26
	v_mul_f32_e32 v67, 0xbfb8aa3b, v67
	v_mul_f32_e32 v69, 0xbfb8aa3b, v69
	v_exp_f32_e32 v67, v67
	v_exp_f32_e32 v70, v69
	v_rcp_f32_e32 v69, v66
	v_add_f32_e32 v64, v60, v28
	v_add_f32_e32 v66, 1.0, v67
	v_add_f32_e32 v67, 1.0, v70
	v_add_f32_e32 v70, v63, v31
	v_mul_f32_e32 v70, 0xbfb8aa3b, v70
	v_exp_f32_e32 v71, v70
	v_add_f32_e32 v70, v59, v27
	v_mul_f32_e32 v64, 0xbfb8aa3b, v64
	v_mul_f32_e32 v70, 0xbfb8aa3b, v70
	v_exp_f32_e32 v64, v64
	v_exp_f32_e32 v72, v70
	v_rcp_f32_e32 v70, v67
	v_add_f32_e32 v67, 1.0, v71
	v_add_f32_e32 v64, 1.0, v64
	v_add_f32_e32 v71, 1.0, v72
	v_rcp_f32_e32 v64, v64
	v_rcp_f32_e32 v65, v65
	v_rcp_f32_e32 v66, v66
	v_rcp_f32_e32 v67, v67
	v_rcp_f32_e32 v71, v71

; __device__ __forceinline__ float sigmoidf_(float x) { return __builtin_amdgcn_rcpf(1.0f + __expf(-x)); }
;     __device__ __forceinline__ void operator()(const f32x4 (&acc)[2][2][4][2], const Unit& u, int wr, int wc, int fr, int fq) const {
;     ...
;                     const int row = row0 + ai * 128 + m * 16;
;                     f32x4 v0 = acc[ai][bj][m][0], v1 = acc[ai][bj][m][1];
;                     if (mode == 0) { v0 = v0 * s0; v1 = v1 * s1; }
;                     else if (mode == 1) {
; #pragma unroll
;                         for (int j = 0; j < 4; ++j) { v0[j] = sigmoidf_(v0[j] + s0[j]); v1[j] = sigmoidf_(v1[j] + s1[j]); } }
;                     else {
;                         v0 = v0 + s0; v1 = v1 + s1;
; #pragma unroll
;                         for (int j = 0; j < 4; ++j) {
;                             v0[j] = __expf(-0.60653066f * sigmoidf_(v0[j])); v1[j] = __expf(-0.60653066f * sigmoidf_(v1[j])); }
;                     }
.LBB0_478:
	s_cmp_lg_u32 s21, 1
	s_cbranch_scc0 .LBB0_480
	s_nop 0
	v_pk_add_f32 v[58:59], v[54:55], v[30:31]
	v_pk_add_f32 v[56:57], v[52:53], v[28:29]
	v_pk_add_f32 v[60:61], v[48:49], v[24:25]
	v_pk_add_f32 v[62:63], v[50:51], v[26:27]
	v_mul_f32_e32 v56, 0xbfb8aa3b, v56
	v_mul_f32_e32 v60, 0xbfb8aa3b, v60
	v_mul_f32_e32 v57, 0xbfb8aa3b, v57
	v_mul_f32_e32 v61, 0xbfb8aa3b, v61
	v_mul_f32_e32 v58, 0xbfb8aa3b, v58
	v_mul_f32_e32 v62, 0xbfb8aa3b, v62
	v_mul_f32_e32 v59, 0xbfb8aa3b, v59
	v_mul_f32_e32 v63, 0xbfb8aa3b, v63
	v_exp_f32_e32 v56, v56
	v_exp_f32_e32 v60, v60
	v_exp_f32_e32 v57, v57
	v_exp_f32_e32 v61, v61
	v_exp_f32_e32 v58, v58
	v_exp_f32_e32 v62, v62
	v_exp_f32_e32 v59, v59
	v_exp_f32_e32 v63, v63
	v_add_f32_e32 v56, 1.0, v56
	v_add_f32_e32 v60, 1.0, v60
	v_add_f32_e32 v57, 1.0, v57
	v_add_f32_e32 v61, 1.0, v61
	v_add_f32_e32 v58, 1.0, v58
	v_add_f32_e32 v62, 1.0, v62
	v_add_f32_e32 v59, 1.0, v59
	v_add_f32_e32 v63, 1.0, v63
	v_rcp_f32_e32 v56, v56
	v_rcp_f32_e32 v60, v60
	v_rcp_f32_e32 v57, v57
	v_rcp_f32_e32 v61, v61
	v_rcp_f32_e32 v58, v58
	v_rcp_f32_e32 v62, v62
	v_rcp_f32_e32 v59, v59
	v_rcp_f32_e32 v63, v63
	v_mul_f32_e32 v56, 0xbf1b4598, v56
	v_mul_f32_e32 v60, 0xbf1b4598, v60
	v_mul_f32_e32 v57, 0xbf1b4598, v57
	v_mul_f32_e32 v61, 0xbf1b4598, v61
	v_mul_f32_e32 v58, 0xbf1b4598, v58
	v_mul_f32_e32 v62, 0xbf1b4598, v62
	v_mul_f32_e32 v59, 0xbf1b4598, v59
	v_mul_f32_e32 v63, 0xbf1b4598, v63
	v_mul_f32_e32 v56, 0x3fb8aa3b, v56
	v_mul_f32_e32 v60, 0x3fb8aa3b, v60
	v_mul_f32_e32 v57, 0x3fb8aa3b, v57
	v_mul_f32_e32 v61, 0x3fb8aa3b, v61
	v_mul_f32_e32 v58, 0x3fb8aa3b, v58
	v_mul_f32_e32 v62, 0x3fb8aa3b, v62
	v_mul_f32_e32 v59, 0x3fb8aa3b, v59
	v_mul_f32_e32 v63, 0x3fb8aa3b, v63
	v_exp_f32_e32 v56, v56
	v_exp_f32_e32 v60, v60
	v_exp_f32_e32 v57, v57
	v_exp_f32_e32 v61, v61
	v_exp_f32_e32 v58, v58
	v_exp_f32_e32 v62, v62
	v_exp_f32_e32 v59, v59
	v_exp_f32_e32 v63, v63
	s_mov_b64 s[4:5], 0
.LBB0_480:
	s_andn2_b64 vcc, exec, s[4:5]
	s_cbranch_vccnz .LBB0_482
	s_nop 0
	v_add_f32_e32 v57, v48, v24
	v_mul_f32_e32 v57, 0xbfb8aa3b, v57
	v_add_f32_e32 v58, v53, v29
	v_add_f32_e32 v59, v49, v25
	v_exp_f32_e32 v57, v57
	v_mul_f32_e32 v58, 0xbfb8aa3b, v58
	v_mul_f32_e32 v59, 0xbfb8aa3b, v59
	v_exp_f32_e32 v58, v58
	v_exp_f32_e32 v59, v59
	v_add_f32_e32 v57, 1.0, v57
	v_rcp_f32_e32 v60, v57
	v_add_f32_e32 v57, 1.0, v58
	v_add_f32_e32 v58, 1.0, v59
	v_add_f32_e32 v59, v54, v30
	v_add_f32_e32 v61, v50, v26
	v_mul_f32_e32 v59, 0xbfb8aa3b, v59
	v_mul_f32_e32 v61, 0xbfb8aa3b, v61
	v_exp_f32_e32 v59, v59
	v_exp_f32_e32 v62, v61
	v_rcp_f32_e32 v61, v58
	v_add_f32_e32 v56, v52, v28
	v_add_f32_e32 v58, 1.0, v59
	v_add_f32_e32 v59, 1.0, v62
	v_add_f32_e32 v62, v55, v31
	v_mul_f32_e32 v62, 0xbfb8aa3b, v62
	v_exp_f32_e32 v63, v62
	v_add_f32_e32 v62, v51, v27
	v_mul_f32_e32 v56, 0xbfb8aa3b, v56
	v_mul_f32_e32 v62, 0xbfb8aa3b, v62
	v_exp_f32_e32 v56, v56
	v_exp_f32_e32 v64, v62
	v_rcp_f32_e32 v62, v59
	v_add_f32_e32 v59, 1.0, v63
	v_add_f32_e32 v56, 1.0, v56
	v_add_f32_e32 v63, 1.0, v64
	v_rcp_f32_e32 v56, v56
	v_rcp_f32_e32 v57, v57
	v_rcp_f32_e32 v58, v58
	v_rcp_f32_e32 v59, v59
	v_rcp_f32_e32 v63, v63

; __device__ __forceinline__ float sigmoidf_(float x) { return __builtin_amdgcn_rcpf(1.0f + __expf(-x)); }
;     __device__ __forceinline__ void operator()(const f32x4 (&acc)[2][2][4][2], const Unit& u, int wr, int wc, int fr, int fq) const {
;     ...
;                     const int row = row0 + ai * 128 + m * 16;
;                     f32x4 v0 = acc[ai][bj][m][0], v1 = acc[ai][bj][m][1];
;                     if (mode == 0) { v0 = v0 * s0; v1 = v1 * s1; }
;                     else if (mode == 1) {
; #pragma unroll
;                         for (int j = 0; j < 4; ++j) { v0[j] = sigmoidf_(v0[j] + s0[j]); v1[j] = sigmoidf_(v1[j] + s1[j]); } }
;                     else {
;                         v0 = v0 + s0; v1 = v1 + s1;
; #pragma unroll
;                         for (int j = 0; j < 4; ++j) {
;                             v0[j] = __expf(-0.60653066f * sigmoidf_(v0[j])); v1[j] = __expf(-0.60653066f * sigmoidf_(v1[j])); }
;                     }
.LBB0_486:
	s_cmp_lg_u32 s21, 1
	s_cbranch_scc0 .LBB0_488
	s_nop 0
	v_pk_add_f32 v[50:51], v[46:47], v[30:31]
	v_pk_add_f32 v[48:49], v[44:45], v[28:29]
	v_pk_add_f32 v[52:53], v[40:41], v[24:25]
	v_pk_add_f32 v[54:55], v[42:43], v[26:27]
	v_mul_f32_e32 v48, 0xbfb8aa3b, v48
	v_mul_f32_e32 v52, 0xbfb8aa3b, v52
	v_mul_f32_e32 v49, 0xbfb8aa3b, v49
	v_mul_f32_e32 v53, 0xbfb8aa3b, v53
	v_mul_f32_e32 v50, 0xbfb8aa3b, v50
	v_mul_f32_e32 v54, 0xbfb8aa3b, v54
	v_mul_f32_e32 v51, 0xbfb8aa3b, v51
	v_mul_f32_e32 v55, 0xbfb8aa3b, v55
	v_exp_f32_e32 v48, v48
	v_exp_f32_e32 v52, v52
	v_exp_f32_e32 v49, v49
	v_exp_f32_e32 v53, v53
	v_exp_f32_e32 v50, v50
	v_exp_f32_e32 v54, v54
	v_exp_f32_e32 v51, v51
	v_exp_f32_e32 v55, v55
	v_add_f32_e32 v48, 1.0, v48
	v_add_f32_e32 v52, 1.0, v52
	v_add_f32_e32 v49, 1.0, v49
	v_add_f32_e32 v53, 1.0, v53
	v_add_f32_e32 v50, 1.0, v50
	v_add_f32_e32 v54, 1.0, v54
	v_add_f32_e32 v51, 1.0, v51
	v_add_f32_e32 v55, 1.0, v55
	v_rcp_f32_e32 v48, v48
	v_rcp_f32_e32 v52, v52
	v_rcp_f32_e32 v49, v49
	v_rcp_f32_e32 v53, v53
	v_rcp_f32_e32 v50, v50
	v_rcp_f32_e32 v54, v54
	v_rcp_f32_e32 v51, v51
	v_rcp_f32_e32 v55, v55
	v_mul_f32_e32 v48, 0xbf1b4598, v48
	v_mul_f32_e32 v52, 0xbf1b4598, v52
	v_mul_f32_e32 v49, 0xbf1b4598, v49
	v_mul_f32_e32 v53, 0xbf1b4598, v53
	v_mul_f32_e32 v50, 0xbf1b4598, v50
	v_mul_f32_e32 v54, 0xbf1b4598, v54
	v_mul_f32_e32 v51, 0xbf1b4598, v51
	v_mul_f32_e32 v55, 0xbf1b4598, v55
	v_mul_f32_e32 v48, 0x3fb8aa3b, v48
	v_mul_f32_e32 v52, 0x3fb8aa3b, v52
	v_mul_f32_e32 v49, 0x3fb8aa3b, v49
	v_mul_f32_e32 v53, 0x3fb8aa3b, v53
	v_mul_f32_e32 v50, 0x3fb8aa3b, v50
	v_mul_f32_e32 v54, 0x3fb8aa3b, v54
	v_mul_f32_e32 v51, 0x3fb8aa3b, v51
	v_mul_f32_e32 v55, 0x3fb8aa3b, v55
	v_exp_f32_e32 v48, v48
	v_exp_f32_e32 v52, v52
	v_exp_f32_e32 v49, v49
	v_exp_f32_e32 v53, v53
	v_exp_f32_e32 v50, v50
	v_exp_f32_e32 v54, v54
	v_exp_f32_e32 v51, v51
	v_exp_f32_e32 v55, v55
	s_mov_b64 s[4:5], 0
.LBB0_488:
	s_andn2_b64 vcc, exec, s[4:5]
	s_cbranch_vccnz .LBB0_490
	s_nop 0
	v_add_f32_e32 v49, v40, v24
	v_mul_f32_e32 v49, 0xbfb8aa3b, v49
	v_add_f32_e32 v50, v45, v29
	v_add_f32_e32 v51, v41, v25
	v_exp_f32_e32 v49, v49
	v_mul_f32_e32 v50, 0xbfb8aa3b, v50
	v_mul_f32_e32 v51, 0xbfb8aa3b, v51
	v_exp_f32_e32 v50, v50
	v_exp_f32_e32 v51, v51
	v_add_f32_e32 v49, 1.0, v49
	v_rcp_f32_e32 v52, v49
	v_add_f32_e32 v49, 1.0, v50
	v_add_f32_e32 v50, 1.0, v51
	v_add_f32_e32 v51, v46, v30
	v_add_f32_e32 v53, v42, v26
	v_mul_f32_e32 v51, 0xbfb8aa3b, v51
	v_mul_f32_e32 v53, 0xbfb8aa3b, v53
	v_exp_f32_e32 v51, v51
	v_exp_f32_e32 v54, v53
	v_rcp_f32_e32 v53, v50
	v_add_f32_e32 v48, v44, v28
	v_add_f32_e32 v50, 1.0, v51
	v_add_f32_e32 v51, 1.0, v54
	v_add_f32_e32 v54, v47, v31
	v_mul_f32_e32 v54, 0xbfb8aa3b, v54
	v_exp_f32_e32 v55, v54
	v_add_f32_e32 v54, v43, v27
	v_mul_f32_e32 v48, 0xbfb8aa3b, v48
	v_mul_f32_e32 v54, 0xbfb8aa3b, v54
	v_exp_f32_e32 v48, v48
	v_exp_f32_e32 v56, v54
	v_rcp_f32_e32 v54, v51
	v_add_f32_e32 v51, 1.0, v55
	v_add_f32_e32 v48, 1.0, v48
	v_add_f32_e32 v55, 1.0, v56
	v_rcp_f32_e32 v48, v48
	v_rcp_f32_e32 v49, v49
	v_rcp_f32_e32 v50, v50
	v_rcp_f32_e32 v51, v51
	v_rcp_f32_e32 v55, v55

; __device__ __forceinline__ float sigmoidf_(float x) { return __builtin_amdgcn_rcpf(1.0f + __expf(-x)); }
;     __device__ __forceinline__ void operator()(const f32x4 (&acc)[2][2][4][2], const Unit& u, int wr, int wc, int fr, int fq) const {
;     ...
;                     const int row = row0 + ai * 128 + m * 16;
;                     f32x4 v0 = acc[ai][bj][m][0], v1 = acc[ai][bj][m][1];
;                     if (mode == 0) { v0 = v0 * s0; v1 = v1 * s1; }
;                     else if (mode == 1) {
; #pragma unroll
;                         for (int j = 0; j < 4; ++j) { v0[j] = sigmoidf_(v0[j] + s0[j]); v1[j] = sigmoidf_(v1[j] + s1[j]); } }
;                     else {
;                         v0 = v0 + s0; v1 = v1 + s1;
; #pragma unroll
;                         for (int j = 0; j < 4; ++j) {
;                             v0[j] = __expf(-0.60653066f * sigmoidf_(v0[j])); v1[j] = __expf(-0.60653066f * sigmoidf_(v1[j])); }
;                     }
.LBB0_494:
	s_cmp_lg_u32 s21, 1
	s_cbranch_scc0 .LBB0_496
	s_nop 0
	v_pk_add_f32 v[42:43], v[38:39], v[30:31]
	v_pk_add_f32 v[40:41], v[36:37], v[28:29]
	v_pk_add_f32 v[44:45], v[32:33], v[24:25]
	v_pk_add_f32 v[46:47], v[34:35], v[26:27]
	v_mul_f32_e32 v40, 0xbfb8aa3b, v40
	v_mul_f32_e32 v44, 0xbfb8aa3b, v44
	v_mul_f32_e32 v41, 0xbfb8aa3b, v41
	v_mul_f32_e32 v45, 0xbfb8aa3b, v45
	v_mul_f32_e32 v42, 0xbfb8aa3b, v42
	v_mul_f32_e32 v46, 0xbfb8aa3b, v46
	v_mul_f32_e32 v43, 0xbfb8aa3b, v43
	v_mul_f32_e32 v47, 0xbfb8aa3b, v47
	v_exp_f32_e32 v40, v40
	v_exp_f32_e32 v44, v44
	v_exp_f32_e32 v41, v41
	v_exp_f32_e32 v45, v45
	v_exp_f32_e32 v42, v42
	v_exp_f32_e32 v46, v46
	v_exp_f32_e32 v43, v43
	v_exp_f32_e32 v47, v47
	v_add_f32_e32 v40, 1.0, v40
	v_add_f32_e32 v44, 1.0, v44
	v_add_f32_e32 v41, 1.0, v41
	v_add_f32_e32 v45, 1.0, v45
	v_add_f32_e32 v42, 1.0, v42
	v_add_f32_e32 v46, 1.0, v46
	v_add_f32_e32 v43, 1.0, v43
	v_add_f32_e32 v47, 1.0, v47
	v_rcp_f32_e32 v40, v40
	v_rcp_f32_e32 v44, v44
	v_rcp_f32_e32 v41, v41
	v_rcp_f32_e32 v45, v45
	v_rcp_f32_e32 v42, v42
	v_rcp_f32_e32 v46, v46
	v_rcp_f32_e32 v43, v43
	v_rcp_f32_e32 v47, v47
	v_mul_f32_e32 v40, 0xbf1b4598, v40
	v_mul_f32_e32 v44, 0xbf1b4598, v44
	v_mul_f32_e32 v41, 0xbf1b4598, v41
	v_mul_f32_e32 v45, 0xbf1b4598, v45
	v_mul_f32_e32 v42, 0xbf1b4598, v42
	v_mul_f32_e32 v46, 0xbf1b4598, v46
	v_mul_f32_e32 v43, 0xbf1b4598, v43
	v_mul_f32_e32 v47, 0xbf1b4598, v47
	v_mul_f32_e32 v40, 0x3fb8aa3b, v40
	v_mul_f32_e32 v44, 0x3fb8aa3b, v44
	v_mul_f32_e32 v41, 0x3fb8aa3b, v41
	v_mul_f32_e32 v45, 0x3fb8aa3b, v45
	v_mul_f32_e32 v42, 0x3fb8aa3b, v42
	v_mul_f32_e32 v46, 0x3fb8aa3b, v46
	v_mul_f32_e32 v43, 0x3fb8aa3b, v43
	v_mul_f32_e32 v47, 0x3fb8aa3b, v47
	v_exp_f32_e32 v40, v40
	v_exp_f32_e32 v44, v44
	v_exp_f32_e32 v41, v41
	v_exp_f32_e32 v45, v45
	v_exp_f32_e32 v42, v42
	v_exp_f32_e32 v46, v46
	v_exp_f32_e32 v43, v43
	v_exp_f32_e32 v47, v47
	s_mov_b64 s[4:5], 0
.LBB0_496:
	s_andn2_b64 vcc, exec, s[4:5]
	s_cbranch_vccnz .LBB0_498
	s_nop 0
	v_add_f32_e32 v41, v32, v24
	v_mul_f32_e32 v41, 0xbfb8aa3b, v41
	v_add_f32_e32 v42, v37, v29
	v_add_f32_e32 v43, v33, v25
	v_exp_f32_e32 v41, v41
	v_mul_f32_e32 v42, 0xbfb8aa3b, v42
	v_mul_f32_e32 v43, 0xbfb8aa3b, v43
	v_exp_f32_e32 v42, v42
	v_exp_f32_e32 v43, v43
	v_add_f32_e32 v41, 1.0, v41
	v_rcp_f32_e32 v44, v41
	v_add_f32_e32 v41, 1.0, v42
	v_add_f32_e32 v42, 1.0, v43
	v_add_f32_e32 v43, v38, v30
	v_add_f32_e32 v45, v34, v26
	v_mul_f32_e32 v43, 0xbfb8aa3b, v43
	v_mul_f32_e32 v45, 0xbfb8aa3b, v45
	v_exp_f32_e32 v43, v43
	v_exp_f32_e32 v46, v45
	v_rcp_f32_e32 v45, v42
	v_add_f32_e32 v40, v36, v28
	v_add_f32_e32 v42, 1.0, v43
	v_add_f32_e32 v43, 1.0, v46
	v_add_f32_e32 v46, v39, v31
	v_mul_f32_e32 v46, 0xbfb8aa3b, v46
	v_exp_f32_e32 v47, v46
	v_add_f32_e32 v46, v35, v27
	v_mul_f32_e32 v40, 0xbfb8aa3b, v40
	v_mul_f32_e32 v46, 0xbfb8aa3b, v46
	v_exp_f32_e32 v40, v40
	v_exp_f32_e32 v48, v46
	v_rcp_f32_e32 v46, v43
	v_add_f32_e32 v43, 1.0, v47
	v_add_f32_e32 v40, 1.0, v40
	v_add_f32_e32 v47, 1.0, v48
	v_rcp_f32_e32 v40, v40
	v_rcp_f32_e32 v41, v41
	v_rcp_f32_e32 v42, v42
	v_rcp_f32_e32 v43, v43
	v_rcp_f32_e32 v47, v47

; __device__ __forceinline__ float sigmoidf_(float x) { return __builtin_amdgcn_rcpf(1.0f + __expf(-x)); }
;     __device__ __forceinline__ void operator()(const f32x4 (&acc)[2][2][4][2], const Unit& u, int wr, int wc, int fr, int fq) const {
;     ...
;                     const int row = row0 + ai * 128 + m * 16;
;                     f32x4 v0 = acc[ai][bj][m][0], v1 = acc[ai][bj][m][1];
;                     if (mode == 0) { v0 = v0 * s0; v1 = v1 * s1; }
;                     else if (mode == 1) {
; #pragma unroll
;                         for (int j = 0; j < 4; ++j) { v0[j] = sigmoidf_(v0[j] + s0[j]); v1[j] = sigmoidf_(v1[j] + s1[j]); } }
;                     else {
;                         v0 = v0 + s0; v1 = v1 + s1;
; #pragma unroll
;                         for (int j = 0; j < 4; ++j) {
;                             v0[j] = __expf(-0.60653066f * sigmoidf_(v0[j])); v1[j] = __expf(-0.60653066f * sigmoidf_(v1[j])); }
;                     }
.LBB0_502:
	s_cmp_lg_u32 s21, 1
	s_cbranch_scc0 .LBB0_504
	s_nop 0
	v_pk_add_f32 v[34:35], v[22:23], v[30:31]
	v_pk_add_f32 v[32:33], v[20:21], v[28:29]
	v_pk_add_f32 v[36:37], v[16:17], v[24:25]
	v_pk_add_f32 v[38:39], v[18:19], v[26:27]
	v_mul_f32_e32 v32, 0xbfb8aa3b, v32
	v_mul_f32_e32 v36, 0xbfb8aa3b, v36
	v_mul_f32_e32 v33, 0xbfb8aa3b, v33
	v_mul_f32_e32 v37, 0xbfb8aa3b, v37
	v_mul_f32_e32 v34, 0xbfb8aa3b, v34
	v_mul_f32_e32 v38, 0xbfb8aa3b, v38
	v_mul_f32_e32 v35, 0xbfb8aa3b, v35
	v_mul_f32_e32 v39, 0xbfb8aa3b, v39
	v_exp_f32_e32 v32, v32
	v_exp_f32_e32 v36, v36
	v_exp_f32_e32 v33, v33
	v_exp_f32_e32 v37, v37
	v_exp_f32_e32 v34, v34
	v_exp_f32_e32 v38, v38
	v_exp_f32_e32 v35, v35
	v_exp_f32_e32 v39, v39
	v_add_f32_e32 v32, 1.0, v32
	v_add_f32_e32 v36, 1.0, v36
	v_add_f32_e32 v33, 1.0, v33
	v_add_f32_e32 v37, 1.0, v37
	v_add_f32_e32 v34, 1.0, v34
	v_add_f32_e32 v38, 1.0, v38
	v_add_f32_e32 v35, 1.0, v35
	v_add_f32_e32 v39, 1.0, v39
	v_rcp_f32_e32 v32, v32
	v_rcp_f32_e32 v36, v36
	v_rcp_f32_e32 v33, v33
	v_rcp_f32_e32 v37, v37
	v_rcp_f32_e32 v34, v34
	v_rcp_f32_e32 v38, v38
	v_rcp_f32_e32 v35, v35
	v_rcp_f32_e32 v39, v39
	v_mul_f32_e32 v32, 0xbf1b4598, v32
	v_mul_f32_e32 v36, 0xbf1b4598, v36
	v_mul_f32_e32 v33, 0xbf1b4598, v33
	v_mul_f32_e32 v37, 0xbf1b4598, v37
	v_mul_f32_e32 v34, 0xbf1b4598, v34
	v_mul_f32_e32 v38, 0xbf1b4598, v38
	v_mul_f32_e32 v35, 0xbf1b4598, v35
	v_mul_f32_e32 v39, 0xbf1b4598, v39
	v_mul_f32_e32 v32, 0x3fb8aa3b, v32
	v_mul_f32_e32 v36, 0x3fb8aa3b, v36
	v_mul_f32_e32 v33, 0x3fb8aa3b, v33
	v_mul_f32_e32 v37, 0x3fb8aa3b, v37
	v_mul_f32_e32 v34, 0x3fb8aa3b, v34
	v_mul_f32_e32 v38, 0x3fb8aa3b, v38
	v_mul_f32_e32 v35, 0x3fb8aa3b, v35
	v_mul_f32_e32 v39, 0x3fb8aa3b, v39
	v_exp_f32_e32 v32, v32
	v_exp_f32_e32 v36, v36
	v_exp_f32_e32 v33, v33
	v_exp_f32_e32 v37, v37
	v_exp_f32_e32 v34, v34
	v_exp_f32_e32 v38, v38
	v_exp_f32_e32 v35, v35
	v_exp_f32_e32 v39, v39
	s_mov_b64 s[4:5], 0
.LBB0_504:
	s_andn2_b64 vcc, exec, s[4:5]
	s_cbranch_vccnz .LBB0_506
	s_nop 0
	v_add_f32_e32 v33, v16, v24
	v_mul_f32_e32 v33, 0xbfb8aa3b, v33
	v_add_f32_e32 v34, v21, v29
	v_add_f32_e32 v35, v17, v25
	v_exp_f32_e32 v33, v33
	v_mul_f32_e32 v34, 0xbfb8aa3b, v34
	v_mul_f32_e32 v35, 0xbfb8aa3b, v35
	v_exp_f32_e32 v34, v34
	v_exp_f32_e32 v35, v35
	v_add_f32_e32 v33, 1.0, v33
	v_rcp_f32_e32 v36, v33
	v_add_f32_e32 v33, 1.0, v34
	v_add_f32_e32 v34, 1.0, v35
	v_add_f32_e32 v35, v22, v30
	v_add_f32_e32 v37, v18, v26
	v_mul_f32_e32 v35, 0xbfb8aa3b, v35
	v_mul_f32_e32 v37, 0xbfb8aa3b, v37
	v_exp_f32_e32 v35, v35
	v_exp_f32_e32 v38, v37
	v_rcp_f32_e32 v37, v34
	v_add_f32_e32 v32, v20, v28
	v_add_f32_e32 v34, 1.0, v35
	v_add_f32_e32 v35, 1.0, v38
	v_add_f32_e32 v38, v23, v31
	v_mul_f32_e32 v38, 0xbfb8aa3b, v38
	v_exp_f32_e32 v39, v38
	v_add_f32_e32 v38, v19, v27
	v_mul_f32_e32 v32, 0xbfb8aa3b, v32
	v_mul_f32_e32 v38, 0xbfb8aa3b, v38
	v_exp_f32_e32 v32, v32
	v_exp_f32_e32 v40, v38
	v_rcp_f32_e32 v38, v35
	v_add_f32_e32 v35, 1.0, v39
	v_add_f32_e32 v32, 1.0, v32
	v_add_f32_e32 v39, 1.0, v40
	v_rcp_f32_e32 v32, v32
	v_rcp_f32_e32 v33, v33
	v_rcp_f32_e32 v34, v34
	v_rcp_f32_e32 v35, v35
	v_rcp_f32_e32 v39, v39

; __device__ __forceinline__ float sigmoidf_(float x) { return __builtin_amdgcn_rcpf(1.0f + __expf(-x)); }
;     __device__ __forceinline__ void operator()(const f32x4 (&acc)[2][2][4][2], const Unit& u, int wr, int wc, int fr, int fq) const {
;     ...
;                     const int row = row0 + ai * 128 + m * 16;
;                     f32x4 v0 = acc[ai][bj][m][0], v1 = acc[ai][bj][m][1];
;                     if (mode == 0) { v0 = v0 * s0; v1 = v1 * s1; }
;                     else if (mode == 1) {
; #pragma unroll
;                         for (int j = 0; j < 4; ++j) { v0[j] = sigmoidf_(v0[j] + s0[j]); v1[j] = sigmoidf_(v1[j] + s1[j]); } }
;                     else {
;                         v0 = v0 + s0; v1 = v1 + s1;
; #pragma unroll
;                         for (int j = 0; j < 4; ++j) {
;                             v0[j] = __expf(-0.60653066f * sigmoidf_(v0[j])); v1[j] = __expf(-0.60653066f * sigmoidf_(v1[j])); }
;                     }
.LBB0_510:
	s_cmp_lg_u32 s21, 1
	s_cbranch_scc0 .LBB0_512
	s_nop 0
	v_pk_add_f32 v[18:19], v[14:15], v[30:31]
	v_pk_add_f32 v[16:17], v[12:13], v[28:29]
	v_pk_add_f32 v[20:21], v[8:9], v[24:25]
	v_pk_add_f32 v[22:23], v[10:11], v[26:27]
	v_mul_f32_e32 v16, 0xbfb8aa3b, v16
	v_mul_f32_e32 v20, 0xbfb8aa3b, v20
	v_mul_f32_e32 v17, 0xbfb8aa3b, v17
	v_mul_f32_e32 v21, 0xbfb8aa3b, v21
	v_mul_f32_e32 v18, 0xbfb8aa3b, v18
	v_mul_f32_e32 v22, 0xbfb8aa3b, v22
	v_mul_f32_e32 v19, 0xbfb8aa3b, v19
	v_mul_f32_e32 v23, 0xbfb8aa3b, v23
	v_exp_f32_e32 v16, v16
	v_exp_f32_e32 v20, v20
	v_exp_f32_e32 v17, v17
	v_exp_f32_e32 v21, v21
	v_exp_f32_e32 v18, v18
	v_exp_f32_e32 v22, v22
	v_exp_f32_e32 v19, v19
	v_exp_f32_e32 v23, v23
	v_add_f32_e32 v16, 1.0, v16
	v_add_f32_e32 v20, 1.0, v20
	v_add_f32_e32 v17, 1.0, v17
	v_add_f32_e32 v21, 1.0, v21
	v_add_f32_e32 v18, 1.0, v18
	v_add_f32_e32 v22, 1.0, v22
	v_add_f32_e32 v19, 1.0, v19
	v_add_f32_e32 v23, 1.0, v23
	v_rcp_f32_e32 v16, v16
	v_rcp_f32_e32 v20, v20
	v_rcp_f32_e32 v17, v17
	v_rcp_f32_e32 v21, v21
	v_rcp_f32_e32 v18, v18
	v_rcp_f32_e32 v22, v22
	v_rcp_f32_e32 v19, v19
	v_rcp_f32_e32 v23, v23
	v_mul_f32_e32 v16, 0xbf1b4598, v16
	v_mul_f32_e32 v20, 0xbf1b4598, v20
	v_mul_f32_e32 v17, 0xbf1b4598, v17
	v_mul_f32_e32 v21, 0xbf1b4598, v21
	v_mul_f32_e32 v18, 0xbf1b4598, v18
	v_mul_f32_e32 v22, 0xbf1b4598, v22
	v_mul_f32_e32 v19, 0xbf1b4598, v19
	v_mul_f32_e32 v23, 0xbf1b4598, v23
	v_mul_f32_e32 v16, 0x3fb8aa3b, v16
	v_mul_f32_e32 v20, 0x3fb8aa3b, v20
	v_mul_f32_e32 v17, 0x3fb8aa3b, v17
	v_mul_f32_e32 v21, 0x3fb8aa3b, v21
	v_mul_f32_e32 v18, 0x3fb8aa3b, v18
	v_mul_f32_e32 v22, 0x3fb8aa3b, v22
	v_mul_f32_e32 v19, 0x3fb8aa3b, v19
	v_mul_f32_e32 v23, 0x3fb8aa3b, v23
	v_exp_f32_e32 v16, v16
	v_exp_f32_e32 v20, v20
	v_exp_f32_e32 v17, v17
	v_exp_f32_e32 v21, v21
	v_exp_f32_e32 v18, v18
	v_exp_f32_e32 v22, v22
	v_exp_f32_e32 v19, v19
	v_exp_f32_e32 v23, v23
	s_mov_b64 s[4:5], 0
.LBB0_512:
	s_andn2_b64 vcc, exec, s[4:5]
	s_cbranch_vccnz .LBB0_514
	s_nop 0
	v_add_f32_e32 v17, v8, v24
	v_mul_f32_e32 v17, 0xbfb8aa3b, v17
	v_add_f32_e32 v18, v13, v29
	v_add_f32_e32 v19, v9, v25
	v_exp_f32_e32 v17, v17
	v_mul_f32_e32 v18, 0xbfb8aa3b, v18
	v_mul_f32_e32 v19, 0xbfb8aa3b, v19
	v_exp_f32_e32 v18, v18
	v_exp_f32_e32 v19, v19
	v_add_f32_e32 v17, 1.0, v17
	v_rcp_f32_e32 v20, v17
	v_add_f32_e32 v17, 1.0, v18
	v_add_f32_e32 v18, 1.0, v19
	v_add_f32_e32 v19, v14, v30
	v_add_f32_e32 v21, v10, v26
	v_mul_f32_e32 v19, 0xbfb8aa3b, v19
	v_mul_f32_e32 v21, 0xbfb8aa3b, v21
	v_exp_f32_e32 v19, v19
	v_exp_f32_e32 v22, v21
	v_rcp_f32_e32 v21, v18
	v_add_f32_e32 v16, v12, v28
	v_add_f32_e32 v18, 1.0, v19
	v_add_f32_e32 v19, 1.0, v22
	v_add_f32_e32 v22, v15, v31
	v_mul_f32_e32 v22, 0xbfb8aa3b, v22
	v_exp_f32_e32 v23, v22
	v_add_f32_e32 v22, v11, v27
	v_mul_f32_e32 v16, 0xbfb8aa3b, v16
	v_mul_f32_e32 v22, 0xbfb8aa3b, v22
	v_exp_f32_e32 v16, v16
	v_exp_f32_e32 v32, v22
	v_rcp_f32_e32 v22, v19
	v_add_f32_e32 v19, 1.0, v23
	v_add_f32_e32 v16, 1.0, v16
	v_add_f32_e32 v23, 1.0, v32
	v_rcp_f32_e32 v16, v16
	v_rcp_f32_e32 v17, v17
	v_rcp_f32_e32 v18, v18
	v_rcp_f32_e32 v19, v19
	v_rcp_f32_e32 v23, v23

; __device__ __forceinline__ float sigmoidf_(float x) { return __builtin_amdgcn_rcpf(1.0f + __expf(-x)); }
;     __device__ __forceinline__ void operator()(const f32x4 (&acc)[2][2][4][2], const Unit& u, int wr, int wc, int fr, int fq) const {
;     ...
;                     const int row = row0 + ai * 128 + m * 16;
;                     f32x4 v0 = acc[ai][bj][m][0], v1 = acc[ai][bj][m][1];
;                     if (mode == 0) { v0 = v0 * s0; v1 = v1 * s1; }
;                     else if (mode == 1) {
; #pragma unroll
;                         for (int j = 0; j < 4; ++j) { v0[j] = sigmoidf_(v0[j] + s0[j]); v1[j] = sigmoidf_(v1[j] + s1[j]); } }
;                     else {
;                         v0 = v0 + s0; v1 = v1 + s1;
; #pragma unroll
;                         for (int j = 0; j < 4; ++j) {
;                             v0[j] = __expf(-0.60653066f * sigmoidf_(v0[j])); v1[j] = __expf(-0.60653066f * sigmoidf_(v1[j])); }
;                     }
.LBB0_518:
	s_cmp_lg_u32 s21, 1
	s_cbranch_scc0 .LBB0_520
	s_nop 0
	v_pk_add_f32 v[10:11], v[6:7], v[30:31]
	v_pk_add_f32 v[8:9], v[4:5], v[28:29]
	v_pk_add_f32 v[12:13], v[0:1], v[24:25]
	v_pk_add_f32 v[14:15], v[2:3], v[26:27]
	v_mul_f32_e32 v8, 0xbfb8aa3b, v8
	v_mul_f32_e32 v12, 0xbfb8aa3b, v12
	v_mul_f32_e32 v9, 0xbfb8aa3b, v9
	v_mul_f32_e32 v13, 0xbfb8aa3b, v13
	v_mul_f32_e32 v10, 0xbfb8aa3b, v10
	v_mul_f32_e32 v14, 0xbfb8aa3b, v14
	v_mul_f32_e32 v11, 0xbfb8aa3b, v11
	v_mul_f32_e32 v15, 0xbfb8aa3b, v15
	v_exp_f32_e32 v8, v8
	v_exp_f32_e32 v12, v12
	v_exp_f32_e32 v9, v9
	v_exp_f32_e32 v13, v13
	v_exp_f32_e32 v10, v10
	v_exp_f32_e32 v14, v14
	v_exp_f32_e32 v11, v11
	v_exp_f32_e32 v15, v15
	v_add_f32_e32 v8, 1.0, v8
	v_add_f32_e32 v12, 1.0, v12
	v_add_f32_e32 v9, 1.0, v9
	v_add_f32_e32 v13, 1.0, v13
	v_add_f32_e32 v10, 1.0, v10
	v_add_f32_e32 v14, 1.0, v14
	v_add_f32_e32 v11, 1.0, v11
	v_add_f32_e32 v15, 1.0, v15
	v_rcp_f32_e32 v8, v8
	v_rcp_f32_e32 v12, v12
	v_rcp_f32_e32 v9, v9
	v_rcp_f32_e32 v13, v13
	v_rcp_f32_e32 v10, v10
	v_rcp_f32_e32 v14, v14
	v_rcp_f32_e32 v11, v11
	v_rcp_f32_e32 v15, v15
	v_mul_f32_e32 v8, 0xbf1b4598, v8
	v_mul_f32_e32 v12, 0xbf1b4598, v12
	v_mul_f32_e32 v9, 0xbf1b4598, v9
	v_mul_f32_e32 v13, 0xbf1b4598, v13
	v_mul_f32_e32 v10, 0xbf1b4598, v10
	v_mul_f32_e32 v14, 0xbf1b4598, v14
	v_mul_f32_e32 v11, 0xbf1b4598, v11
	v_mul_f32_e32 v15, 0xbf1b4598, v15
	v_mul_f32_e32 v8, 0x3fb8aa3b, v8
	v_mul_f32_e32 v12, 0x3fb8aa3b, v12
	v_mul_f32_e32 v9, 0x3fb8aa3b, v9
	v_mul_f32_e32 v13, 0x3fb8aa3b, v13
	v_mul_f32_e32 v10, 0x3fb8aa3b, v10
	v_mul_f32_e32 v14, 0x3fb8aa3b, v14
	v_mul_f32_e32 v11, 0x3fb8aa3b, v11
	v_mul_f32_e32 v15, 0x3fb8aa3b, v15
	v_exp_f32_e32 v8, v8
	v_exp_f32_e32 v12, v12
	v_exp_f32_e32 v9, v9
	v_exp_f32_e32 v13, v13
	v_exp_f32_e32 v10, v10
	v_exp_f32_e32 v14, v14
	v_exp_f32_e32 v11, v11
	v_exp_f32_e32 v15, v15
	s_mov_b64 s[4:5], 0
.LBB0_520:
	s_andn2_b64 vcc, exec, s[4:5]
	s_cbranch_vccnz .LBB0_522
	s_nop 0
	v_add_f32_e32 v9, v0, v24
	v_mul_f32_e32 v9, 0xbfb8aa3b, v9
	v_add_f32_e32 v10, v5, v29
	v_add_f32_e32 v11, v1, v25
	v_exp_f32_e32 v9, v9
	v_mul_f32_e32 v10, 0xbfb8aa3b, v10
	v_mul_f32_e32 v11, 0xbfb8aa3b, v11
	v_exp_f32_e32 v10, v10
	v_exp_f32_e32 v11, v11
	v_add_f32_e32 v9, 1.0, v9
	v_rcp_f32_e32 v12, v9
	v_add_f32_e32 v9, 1.0, v10
	v_add_f32_e32 v10, 1.0, v11
	v_add_f32_e32 v11, v6, v30
	v_add_f32_e32 v13, v2, v26
	v_mul_f32_e32 v11, 0xbfb8aa3b, v11
	v_mul_f32_e32 v13, 0xbfb8aa3b, v13
	v_exp_f32_e32 v11, v11
	v_exp_f32_e32 v14, v13
	v_rcp_f32_e32 v13, v10
	v_add_f32_e32 v8, v4, v28
	v_add_f32_e32 v10, 1.0, v11
	v_add_f32_e32 v11, 1.0, v14
	v_add_f32_e32 v14, v7, v31
	v_mul_f32_e32 v14, 0xbfb8aa3b, v14
	v_exp_f32_e32 v15, v14
	v_add_f32_e32 v14, v3, v27
	v_mul_f32_e32 v8, 0xbfb8aa3b, v8
	v_mul_f32_e32 v14, 0xbfb8aa3b, v14
	v_exp_f32_e32 v8, v8
	v_exp_f32_e32 v16, v14
	v_rcp_f32_e32 v14, v11
	v_add_f32_e32 v11, 1.0, v15
	v_add_f32_e32 v8, 1.0, v8
	v_add_f32_e32 v15, 1.0, v16
	v_rcp_f32_e32 v8, v8
	v_rcp_f32_e32 v9, v9
	v_rcp_f32_e32 v10, v10
	v_rcp_f32_e32 v11, v11
	v_rcp_f32_e32 v15, v15

;     __device__ __forceinline__ void operator()(const f32x4 (&acc)[2][2][4][2], const Unit& u, int wr, int wc, int fr, int fq) const {
;     ...
; #pragma unroll
;                 for (int m = 0; m < 4; ++m) {
;                     const int row = row0 + ai * 128 + m * 16;
;                     f32x4 v0 = acc[ai][bj][m][0], v1 = acc[ai][bj][m][1];
;                     if (mode == 0) { v0 = v0 * s0; v1 = v1 * s1; }
.LBB0_530:
	s_nop 0
	v_pk_mul_f32 v[130:131], v[126:127], v[102:103]
	v_pk_mul_f32 v[128:129], v[124:125], v[100:101]
	v_pk_mul_f32 v[134:135], v[122:123], v[98:99]
	v_pk_mul_f32 v[132:133], v[120:121], v[96:97]
	v_or_b32_e32 v136, 32, v162
	s_and_b64 vcc, exec, s[6:7]
	s_mov_b64 s[4:5], -1
	s_cbranch_vccz .LBB0_420

;     __device__ __forceinline__ void operator()(const f32x4 (&acc)[2][2][4][2], const Unit& u, int wr, int wc, int fr, int fq) const {
;     ...
; #pragma unroll
;                 for (int m = 0; m < 4; ++m) {
;                     const int row = row0 + ai * 128 + m * 16;
;                     f32x4 v0 = acc[ai][bj][m][0], v1 = acc[ai][bj][m][1];
;                     if (mode == 0) { v0 = v0 * s0; v1 = v1 * s1; }
.LBB0_536:
	s_nop 0
	v_pk_mul_f32 v[122:123], v[118:119], v[102:103]
	v_pk_mul_f32 v[120:121], v[116:117], v[100:101]
	v_pk_mul_f32 v[126:127], v[114:115], v[98:99]
	v_pk_mul_f32 v[124:125], v[112:113], v[96:97]
	v_or_b32_e32 v128, 48, v162
	s_and_b64 vcc, exec, s[6:7]
	s_mov_b64 s[4:5], -1
	s_cbranch_vccz .LBB0_428

;     __device__ __forceinline__ void operator()(const f32x4 (&acc)[2][2][4][2], const Unit& u, int wr, int wc, int fr, int fq) const {
;     ...
; #pragma unroll
;                 for (int m = 0; m < 4; ++m) {
;                     const int row = row0 + ai * 128 + m * 16;
;                     f32x4 v0 = acc[ai][bj][m][0], v1 = acc[ai][bj][m][1];
;                     if (mode == 0) { v0 = v0 * s0; v1 = v1 * s1; }
.LBB0_542:
	s_nop 0
	v_pk_mul_f32 v[114:115], v[110:111], v[102:103]
	v_pk_mul_f32 v[112:113], v[108:109], v[100:101]
	v_pk_mul_f32 v[118:119], v[106:107], v[98:99]
	v_pk_mul_f32 v[116:117], v[104:105], v[96:97]
	v_add_u32_e32 v120, 0x80, v162
	s_and_b64 vcc, exec, s[6:7]
	s_mov_b64 s[4:5], -1
	s_cbranch_vccz .LBB0_436

;     __device__ __forceinline__ void operator()(const f32x4 (&acc)[2][2][4][2], const Unit& u, int wr, int wc, int fr, int fq) const {
;     ...
; #pragma unroll
;                 for (int m = 0; m < 4; ++m) {
;                     const int row = row0 + ai * 128 + m * 16;
;                     f32x4 v0 = acc[ai][bj][m][0], v1 = acc[ai][bj][m][1];
;                     if (mode == 0) { v0 = v0 * s0; v1 = v1 * s1; }
.LBB0_548:
	s_nop 0
	v_pk_mul_f32 v[106:107], v[94:95], v[102:103]
	v_pk_mul_f32 v[104:105], v[92:93], v[100:101]
	v_pk_mul_f32 v[110:111], v[90:91], v[98:99]
	v_pk_mul_f32 v[108:109], v[88:89], v[96:97]
	v_add_u32_e32 v112, 0x90, v162
	s_and_b64 vcc, exec, s[6:7]
	s_mov_b64 s[4:5], -1
	s_cbranch_vccz .LBB0_444

;     __device__ __forceinline__ void operator()(const f32x4 (&acc)[2][2][4][2], const Unit& u, int wr, int wc, int fr, int fq) const {
;     ...
; #pragma unroll
;                 for (int m = 0; m < 4; ++m) {
;                     const int row = row0 + ai * 128 + m * 16;
;                     f32x4 v0 = acc[ai][bj][m][0], v1 = acc[ai][bj][m][1];
;                     if (mode == 0) { v0 = v0 * s0; v1 = v1 * s1; }
.LBB0_554:
	s_nop 0
	v_pk_mul_f32 v[90:91], v[86:87], v[102:103]
	v_pk_mul_f32 v[88:89], v[84:85], v[100:101]
	v_pk_mul_f32 v[94:95], v[82:83], v[98:99]
	v_pk_mul_f32 v[92:93], v[80:81], v[96:97]
	v_add_u32_e32 v104, 0xa0, v162
	s_and_b64 vcc, exec, s[6:7]
	s_mov_b64 s[4:5], -1
	s_cbranch_vccz .LBB0_452

;     __device__ __forceinline__ void operator()(const f32x4 (&acc)[2][2][4][2], const Unit& u, int wr, int wc, int fr, int fq) const {
;     ...
; #pragma unroll
;                 for (int m = 0; m < 4; ++m) {
;                     const int row = row0 + ai * 128 + m * 16;
;                     f32x4 v0 = acc[ai][bj][m][0], v1 = acc[ai][bj][m][1];
;                     if (mode == 0) { v0 = v0 * s0; v1 = v1 * s1; }
.LBB0_560:
	s_nop 0
	v_pk_mul_f32 v[82:83], v[78:79], v[102:103]
	v_pk_mul_f32 v[80:81], v[76:77], v[100:101]
	v_pk_mul_f32 v[86:87], v[74:75], v[98:99]
	v_pk_mul_f32 v[84:85], v[72:73], v[96:97]
	v_add_u32_e32 v88, 0xb0, v162
	s_and_b64 vcc, exec, s[6:7]
	s_mov_b64 s[4:5], -1
	s_cbranch_vccz .LBB0_460

;     __device__ __forceinline__ void operator()(const f32x4 (&acc)[2][2][4][2], const Unit& u, int wr, int wc, int fr, int fq) const {
;     ...
; #pragma unroll
;                 for (int m = 0; m < 4; ++m) {
;                     const int row = row0 + ai * 128 + m * 16;
;                     f32x4 v0 = acc[ai][bj][m][0], v1 = acc[ai][bj][m][1];
;                     if (mode == 0) { v0 = v0 * s0; v1 = v1 * s1; }
.LBB0_566:
	s_nop 0
	v_pk_mul_f32 v[74:75], v[70:71], v[30:31]
	v_pk_mul_f32 v[72:73], v[68:69], v[28:29]
	v_pk_mul_f32 v[78:79], v[66:67], v[26:27]
	v_pk_mul_f32 v[76:77], v[64:65], v[24:25]
	s_and_b64 vcc, exec, s[6:7]
	s_mov_b64 s[4:5], -1
	s_cbranch_vccz .LBB0_468

;     __device__ __forceinline__ void operator()(const f32x4 (&acc)[2][2][4][2], const Unit& u, int wr, int wc, int fr, int fq) const {
;     ...
; #pragma unroll
;                 for (int m = 0; m < 4; ++m) {
;                     const int row = row0 + ai * 128 + m * 16;
;                     f32x4 v0 = acc[ai][bj][m][0], v1 = acc[ai][bj][m][1];
;                     if (mode == 0) { v0 = v0 * s0; v1 = v1 * s1; }
.LBB0_572:
	s_nop 0
	v_pk_mul_f32 v[66:67], v[62:63], v[30:31]
	v_pk_mul_f32 v[64:65], v[60:61], v[28:29]
	v_pk_mul_f32 v[70:71], v[58:59], v[26:27]
	v_pk_mul_f32 v[68:69], v[56:57], v[24:25]
	s_and_b64 vcc, exec, s[6:7]
	s_mov_b64 s[4:5], -1
	s_cbranch_vccz .LBB0_476

;     __device__ __forceinline__ void operator()(const f32x4 (&acc)[2][2][4][2], const Unit& u, int wr, int wc, int fr, int fq) const {
;     ...
; #pragma unroll
;                 for (int m = 0; m < 4; ++m) {
;                     const int row = row0 + ai * 128 + m * 16;
;                     f32x4 v0 = acc[ai][bj][m][0], v1 = acc[ai][bj][m][1];
;                     if (mode == 0) { v0 = v0 * s0; v1 = v1 * s1; }
.LBB0_578:
	s_nop 0
	v_pk_mul_f32 v[58:59], v[54:55], v[30:31]
	v_pk_mul_f32 v[56:57], v[52:53], v[28:29]
	v_pk_mul_f32 v[62:63], v[50:51], v[26:27]
	v_pk_mul_f32 v[60:61], v[48:49], v[24:25]
	s_and_b64 vcc, exec, s[6:7]
	s_mov_b64 s[4:5], -1
	s_cbranch_vccz .LBB0_484

;     __device__ __forceinline__ void operator()(const f32x4 (&acc)[2][2][4][2], const Unit& u, int wr, int wc, int fr, int fq) const {
;     ...
; #pragma unroll
;                 for (int m = 0; m < 4; ++m) {
;                     const int row = row0 + ai * 128 + m * 16;
;                     f32x4 v0 = acc[ai][bj][m][0], v1 = acc[ai][bj][m][1];
;                     if (mode == 0) { v0 = v0 * s0; v1 = v1 * s1; }
.LBB0_584:
	s_nop 0
	v_pk_mul_f32 v[50:51], v[46:47], v[30:31]
	v_pk_mul_f32 v[48:49], v[44:45], v[28:29]
	v_pk_mul_f32 v[54:55], v[42:43], v[26:27]
	v_pk_mul_f32 v[52:53], v[40:41], v[24:25]
	s_and_b64 vcc, exec, s[6:7]
	s_mov_b64 s[4:5], -1
	s_cbranch_vccz .LBB0_492

;     __device__ __forceinline__ void operator()(const f32x4 (&acc)[2][2][4][2], const Unit& u, int wr, int wc, int fr, int fq) const {
;     ...
; #pragma unroll
;                 for (int m = 0; m < 4; ++m) {
;                     const int row = row0 + ai * 128 + m * 16;
;                     f32x4 v0 = acc[ai][bj][m][0], v1 = acc[ai][bj][m][1];
;                     if (mode == 0) { v0 = v0 * s0; v1 = v1 * s1; }
.LBB0_590:
	s_nop 0
	v_pk_mul_f32 v[42:43], v[38:39], v[30:31]
	v_pk_mul_f32 v[40:41], v[36:37], v[28:29]
	v_pk_mul_f32 v[46:47], v[34:35], v[26:27]
	v_pk_mul_f32 v[44:45], v[32:33], v[24:25]
	s_and_b64 vcc, exec, s[6:7]
	s_mov_b64 s[4:5], -1
	s_cbranch_vccz .LBB0_500

;     __device__ __forceinline__ void operator()(const f32x4 (&acc)[2][2][4][2], const Unit& u, int wr, int wc, int fr, int fq) const {
;     ...
; #pragma unroll
;                 for (int m = 0; m < 4; ++m) {
;                     const int row = row0 + ai * 128 + m * 16;
;                     f32x4 v0 = acc[ai][bj][m][0], v1 = acc[ai][bj][m][1];
;                     if (mode == 0) { v0 = v0 * s0; v1 = v1 * s1; }
.LBB0_596:
	s_nop 0
	v_pk_mul_f32 v[34:35], v[22:23], v[30:31]
	v_pk_mul_f32 v[32:33], v[20:21], v[28:29]
	v_pk_mul_f32 v[38:39], v[18:19], v[26:27]
	v_pk_mul_f32 v[36:37], v[16:17], v[24:25]
	s_and_b64 vcc, exec, s[6:7]
	s_mov_b64 s[4:5], -1
	s_cbranch_vccz .LBB0_508

;     __device__ __forceinline__ void operator()(const f32x4 (&acc)[2][2][4][2], const Unit& u, int wr, int wc, int fr, int fq) const {
;     ...
; #pragma unroll
;                 for (int m = 0; m < 4; ++m) {
;                     const int row = row0 + ai * 128 + m * 16;
;                     f32x4 v0 = acc[ai][bj][m][0], v1 = acc[ai][bj][m][1];
;                     if (mode == 0) { v0 = v0 * s0; v1 = v1 * s1; }
.LBB0_602:
	s_nop 0
	v_pk_mul_f32 v[18:19], v[14:15], v[30:31]
	v_pk_mul_f32 v[16:17], v[12:13], v[28:29]
	v_pk_mul_f32 v[22:23], v[10:11], v[26:27]
	v_pk_mul_f32 v[20:21], v[8:9], v[24:25]
	s_and_b64 vcc, exec, s[6:7]
	s_mov_b64 s[4:5], -1
	s_cbranch_vccz .LBB0_516

;     __device__ __forceinline__ void operator()(const f32x4 (&acc)[2][2][4][2], const Unit& u, int wr, int wc, int fr, int fq) const {
;     ...
; #pragma unroll
;                 for (int m = 0; m < 4; ++m) {
;                     const int row = row0 + ai * 128 + m * 16;
;                     f32x4 v0 = acc[ai][bj][m][0], v1 = acc[ai][bj][m][1];
;                     if (mode == 0) { v0 = v0 * s0; v1 = v1 * s1; }
.LBB0_608:
	s_nop 0
	v_pk_mul_f32 v[10:11], v[6:7], v[30:31]
	v_pk_mul_f32 v[8:9], v[4:5], v[28:29]
	v_pk_mul_f32 v[14:15], v[2:3], v[26:27]
	v_pk_mul_f32 v[12:13], v[0:1], v[24:25]
	s_and_b64 vcc, exec, s[6:7]
	s_mov_b64 s[4:5], -1
	s_cbranch_vccz .LBB0_524

; #define EPIDN_LOAD(DST, IDX) do { const float* xr_ = out + (size_t)(row0 + ((IDX) >> 2) * 128 + ((IDX) & 3) * 16) * D + col0; \
;             _Pragma("unroll") for (int bj = 0; bj < 2; ++bj) _Pragma("unroll") for (int n = 0; n < 2; ++n) DST[bj][n] = *(const f32x4*)(xr_ + bj * 128 + n * 16); } while (0)
;     __device__ __forceinline__ void operator()(f32x4 (&acc)[2][2][4][2], const Unit& u, int wr, int wc, int fr, int fq) const {
;     ...
;         EPIDN_LOAD(xv, 0);
; #pragma unroll
;         for (int idx = 0; idx < 8; ++idx) {
;             const int ai = idx >> 2, m = idx & 3;
;             if (idx + 1 < 8) EPIDN_LOAD(xn, idx + 1);
;             const int row = row0 + ai * 128 + m * 16; float s = 0.f;
; #pragma unroll
;             for (int bj = 0; bj < 2; ++bj)
; #pragma unroll
;                 for (int n = 0; n < 2; ++n) {
;                     const f32x4 x2 = acc[ai][bj][m][n] + xv[bj][n]; acc[ai][bj][m][n] = x2;
;                     s += (x2[0] * x2[0] + x2[1] * x2[1]) + (x2[2] * x2[2] + x2[3] * x2[3]);
;                 }
;             s += __shfl_xor(s, 16); s += __shfl_xor(s, 32);
;             if (fq == 0) chk += unsafeAtomicAdd(rowsq + row, s);
.LBB0_1322:
	s_add_u32 s0, s90, 0x10b48400
	s_addc_u32 s1, s91, 0
	s_lshl_b32 s4, s14, 8
	s_add_i32 s4, s4, s34
	v_lshlrev_b32_e32 v128, 2, v182
	v_or_b32_e32 v176, s4, v183
	v_lshl_or_b32 v128, s38, 8, v128
	v_or_b32_e32 v144, s35, v128
	v_ashrrev_i32_e32 v177, 31, v176
	v_lshlrev_b64 v[128:129], 13, v[176:177]
	v_ashrrev_i32_e32 v145, 31, v144
	v_lshl_add_u64 v[146:147], s[88:89], 0, v[128:129]
	v_lshlrev_b64 v[128:129], 2, v[144:145]
	v_lshl_add_u64 v[148:149], v[146:147], 0, v[128:129]
	s_barrier
	global_load_dwordx4 v[154:157], v[148:149], off
	global_load_dwordx4 v[158:161], v[148:149], off offset:64
	global_load_dwordx4 v[162:165], v[148:149], off offset:512
	global_load_dwordx4 v[166:169], v[148:149], off offset:576
	v_or_b32_e32 v130, 16, v176
	v_ashrrev_i32_e32 v131, 31, v130
	v_lshlrev_b64 v[130:131], 13, v[130:131]
	v_lshl_add_u64 v[130:131], s[88:89], 0, v[130:131]
	v_lshl_add_u64 v[150:151], v[130:131], 0, v[128:129]
	global_load_dwordx4 v[140:143], v[150:151], off
	global_load_dwordx4 v[136:139], v[150:151], off offset:64
	global_load_dwordx4 v[132:135], v[150:151], off offset:512
	global_load_dwordx4 v[128:131], v[150:151], off offset:576
	v_mbcnt_lo_u32_b32 v152, -1, 0
	v_mbcnt_hi_u32_b32 v170, -1, v152
	v_and_b32_e32 v153, 64, v170
	v_xor_b32_e32 v152, 16, v170
	v_add_u32_e32 v171, 64, v153
	v_cmp_lt_i32_e32 vcc, v152, v171
	v_mov_b32_e32 v190, 0
	v_lshl_add_u64 v[174:175], v[176:177], 2, s[0:1]
	v_cndmask_b32_e32 v152, v170, v152, vcc
	v_lshlrev_b32_e32 v189, 2, v152
	s_waitcnt vmcnt(0)
	v_pk_add_f32 v[152:153], v[126:127], v[156:157]
	v_pk_add_f32 v[154:155], v[124:125], v[154:155]
	v_pk_add_f32 v[156:157], v[122:123], v[160:161]
	v_pk_add_f32 v[158:159], v[120:121], v[158:159]
	v_pk_add_f32 v[160:161], v[118:119], v[164:165]
	v_pk_add_f32 v[162:163], v[116:117], v[162:163]
	v_pk_add_f32 v[164:165], v[114:115], v[168:169]
	v_pk_add_f32 v[166:167], v[112:113], v[166:167]
	v_mul_f32_e32 v112, v155, v155
	v_mul_f32_e32 v113, v153, v153
	v_mul_f32_e32 v114, v159, v159
	v_mul_f32_e32 v115, v157, v157
	v_mul_f32_e32 v116, v163, v163
	v_mul_f32_e32 v117, v161, v161
	v_fmac_f32_e32 v112, v154, v154
	v_fmac_f32_e32 v113, v152, v152
	v_fmac_f32_e32 v114, v158, v158
	v_fmac_f32_e32 v115, v156, v156
	v_mul_f32_e32 v118, v167, v167
	v_mul_f32_e32 v119, v165, v165
	v_fmac_f32_e32 v116, v162, v162
	v_fmac_f32_e32 v117, v160, v160
	v_add_f32_e32 v112, v112, v113
	v_add_f32_e32 v113, v114, v115
	v_fmac_f32_e32 v118, v166, v166
	v_fmac_f32_e32 v119, v164, v164
	v_add_f32_e32 v114, v116, v117
	v_add_f32_e32 v112, v112, v113
	v_add_f32_e32 v112, v112, v114
	v_add_f32_e32 v113, v118, v119
	v_add_f32_e32 v112, v112, v113
	ds_bpermute_b32 v113, v189, v112
	v_xor_b32_e32 v114, 32, v170
	v_cmp_lt_i32_e32 vcc, v114, v171
	s_waitcnt lgkmcnt(0)
	v_add_f32_e32 v112, v112, v113
	v_cndmask_b32_e32 v114, v170, v114, vcc
	v_lshlrev_b32_e32 v191, 2, v114
	ds_bpermute_b32 v113, v191, v112
	v_cmp_eq_u32_e32 vcc, 0, v182
	s_and_saveexec_b64 s[4:5], vcc
	s_cbranch_execz .LBB0_1324
	s_waitcnt lgkmcnt(0)
	v_add_f32_e32 v112, v112, v113
	global_atomic_add_f32 v190, v[174:175], v112, off sc0
	s_nop 0
	s_nop 0
.LBB0_1324:
	s_or_b64 exec, exec, s[4:5]
	v_or_b32_e32 v112, 32, v176
	s_waitcnt lgkmcnt(0)
	v_ashrrev_i32_e32 v113, 31, v112
	v_lshlrev_b64 v[112:113], 13, v[112:113]
	v_lshl_add_u64 v[112:113], s[88:89], 0, v[112:113]
	v_lshl_add_u64 v[168:169], v[144:145], 2, v[112:113]
	global_load_dwordx4 v[124:127], v[168:169], off
	global_load_dwordx4 v[120:123], v[168:169], off offset:64
	global_load_dwordx4 v[116:119], v[168:169], off offset:512
	global_load_dwordx4 v[112:115], v[168:169], off offset:576
	v_pk_add_f32 v[142:143], v[110:111], v[142:143]
	v_pk_add_f32 v[140:141], v[108:109], v[140:141]
	v_pk_add_f32 v[138:139], v[106:107], v[138:139]
	v_pk_add_f32 v[136:137], v[104:105], v[136:137]
	v_mul_f32_e32 v108, v141, v141
	v_mul_f32_e32 v109, v143, v143
	v_mul_f32_e32 v104, v137, v137
	v_mul_f32_e32 v105, v139, v139
	v_pk_add_f32 v[134:135], v[102:103], v[134:135]
	v_pk_add_f32 v[132:133], v[100:101], v[132:133]
	v_fmac_f32_e32 v108, v140, v140
	v_fmac_f32_e32 v109, v142, v142
	v_fmac_f32_e32 v104, v136, v136
	v_fmac_f32_e32 v105, v138, v138
	v_mul_f32_e32 v100, v133, v133
	v_mul_f32_e32 v101, v135, v135
	v_pk_add_f32 v[130:131], v[98:99], v[130:131]
	v_pk_add_f32 v[170:171], v[96:97], v[128:129]
	v_add_f32_e32 v108, v108, v109
	v_add_f32_e32 v104, v104, v105
	v_fmac_f32_e32 v100, v132, v132
	v_fmac_f32_e32 v101, v134, v134
	v_mul_f32_e32 v96, v171, v171
	v_mul_f32_e32 v97, v131, v131
	v_add_f32_e32 v104, v108, v104
	v_add_f32_e32 v100, v100, v101
	v_fmac_f32_e32 v96, v170, v170
	v_fmac_f32_e32 v97, v130, v130
	v_add_f32_e32 v100, v104, v100
	v_add_f32_e32 v96, v96, v97
	v_add_f32_e32 v96, v100, v96
	ds_bpermute_b32 v97, v189, v96
	s_waitcnt lgkmcnt(0)
	v_add_f32_e32 v96, v96, v97
	ds_bpermute_b32 v97, v191, v96
	s_and_saveexec_b64 s[4:5], vcc
	s_cbranch_execz .LBB0_1326
	s_waitcnt lgkmcnt(0)
	v_add_f32_e32 v96, v96, v97
	global_atomic_add_f32 v190, v[174:175], v96, off offset:64 sc0
	s_nop 0
	s_nop 0
; #define EPIDN_LOAD(DST, IDX) do { const float* xr_ = out + (size_t)(row0 + ((IDX) >> 2) * 128 + ((IDX) & 3) * 16) * D + col0; \
;             _Pragma("unroll") for (int bj = 0; bj < 2; ++bj) _Pragma("unroll") for (int n = 0; n < 2; ++n) DST[bj][n] = *(const f32x4*)(xr_ + bj * 128 + n * 16); } while (0)
;     __device__ __forceinline__ void operator()(f32x4 (&acc)[2][2][4][2], const Unit& u, int wr, int wc, int fr, int fq) const {
;     ...
;         for (int idx = 0; idx < 8; ++idx) {
;             const int ai = idx >> 2, m = idx & 3;
;             if (idx + 1 < 8) EPIDN_LOAD(xn, idx + 1);
;             const int row = row0 + ai * 128 + m * 16; float s = 0.f;
; #pragma unroll
;             for (int bj = 0; bj < 2; ++bj)
; #pragma unroll
;                 for (int n = 0; n < 2; ++n) {
;                     const f32x4 x2 = acc[ai][bj][m][n] + xv[bj][n]; acc[ai][bj][m][n] = x2;
;                     s += (x2[0] * x2[0] + x2[1] * x2[1]) + (x2[2] * x2[2] + x2[3] * x2[3]);
;                 }
;             s += __shfl_xor(s, 16); s += __shfl_xor(s, 32);
;             if (fq == 0) chk += unsafeAtomicAdd(rowsq + row, s);
; #pragma unroll
;             for (int bj = 0; bj < 2; ++bj)
; #pragma unroll
;                 for (int n = 0; n < 2; ++n) xv[bj][n] = xn[bj][n];
;         }
.LBB0_1326:
	s_or_b64 exec, exec, s[4:5]
	v_or_b32_e32 v96, 48, v176
	s_waitcnt lgkmcnt(0)
	v_ashrrev_i32_e32 v97, 31, v96
	v_lshlrev_b64 v[96:97], 13, v[96:97]
	v_lshl_add_u64 v[96:97], s[88:89], 0, v[96:97]
	v_lshl_add_u64 v[128:129], v[144:145], 2, v[96:97]
	global_load_dwordx4 v[108:111], v[128:129], off
	global_load_dwordx4 v[104:107], v[128:129], off offset:64
	global_load_dwordx4 v[100:103], v[128:129], off offset:512
	global_load_dwordx4 v[96:99], v[128:129], off offset:576
	s_waitcnt vmcnt(8)
	v_pk_add_f32 v[126:127], v[94:95], v[126:127]
	v_pk_add_f32 v[124:125], v[92:93], v[124:125]
	s_waitcnt vmcnt(7)
	v_pk_add_f32 v[122:123], v[90:91], v[122:123]
	v_pk_add_f32 v[120:121], v[88:89], v[120:121]
	v_mul_f32_e32 v92, v125, v125
	v_mul_f32_e32 v93, v127, v127
	v_mul_f32_e32 v88, v121, v121
	v_mul_f32_e32 v89, v123, v123
	s_waitcnt vmcnt(6)
	v_pk_add_f32 v[118:119], v[86:87], v[118:119]
	v_pk_add_f32 v[116:117], v[84:85], v[116:117]
	v_fmac_f32_e32 v92, v124, v124
	v_fmac_f32_e32 v93, v126, v126
	v_fmac_f32_e32 v88, v120, v120
	v_fmac_f32_e32 v89, v122, v122
	v_mul_f32_e32 v84, v117, v117
	v_mul_f32_e32 v85, v119, v119
	s_waitcnt vmcnt(5)
	v_pk_add_f32 v[114:115], v[82:83], v[114:115]
	v_pk_add_f32 v[172:173], v[80:81], v[112:113]
	v_add_f32_e32 v92, v92, v93
	v_add_f32_e32 v88, v88, v89
	v_fmac_f32_e32 v84, v116, v116
	v_fmac_f32_e32 v85, v118, v118
	v_mul_f32_e32 v80, v173, v173
	v_mul_f32_e32 v81, v115, v115
	v_add_f32_e32 v88, v92, v88
	v_add_f32_e32 v84, v84, v85
	v_fmac_f32_e32 v80, v172, v172
	v_fmac_f32_e32 v81, v114, v114
	v_add_f32_e32 v84, v88, v84
	v_add_f32_e32 v80, v80, v81
	v_add_f32_e32 v80, v84, v80
	ds_bpermute_b32 v81, v189, v80
	s_waitcnt lgkmcnt(0)
	v_add_f32_e32 v80, v80, v81
	ds_bpermute_b32 v81, v191, v80
	s_and_saveexec_b64 s[4:5], vcc
	s_cbranch_execz .LBB0_1328
	s_waitcnt lgkmcnt(0)
	v_add_f32_e32 v80, v80, v81
	global_atomic_add_f32 v190, v[174:175], v80, off offset:128 sc0
	s_nop 0
	s_nop 0
.LBB0_1328:
	s_or_b64 exec, exec, s[4:5]
	v_add_u32_e32 v176, 0x80, v176
	v_ashrrev_i32_e32 v177, 31, v176
	s_waitcnt lgkmcnt(0)
	v_lshlrev_b64 v[80:81], 13, v[176:177]
	v_lshl_add_u64 v[80:81], s[88:89], 0, v[80:81]
	v_lshl_add_u64 v[112:113], v[144:145], 2, v[80:81]
	global_load_dwordx4 v[92:95], v[112:113], off
	global_load_dwordx4 v[88:91], v[112:113], off offset:64
	global_load_dwordx4 v[84:87], v[112:113], off offset:512
	global_load_dwordx4 v[80:83], v[112:113], off offset:576
	s_waitcnt vmcnt(8)
	v_pk_add_f32 v[110:111], v[78:79], v[110:111]
	v_pk_add_f32 v[108:109], v[76:77], v[108:109]
	s_waitcnt vmcnt(7)
	v_pk_add_f32 v[106:107], v[74:75], v[106:107]
	v_pk_add_f32 v[104:105], v[72:73], v[104:105]
	v_mul_f32_e32 v76, v109, v109
	v_mul_f32_e32 v77, v111, v111
	v_mul_f32_e32 v72, v105, v105
	v_mul_f32_e32 v73, v107, v107
	s_waitcnt vmcnt(6)
	v_pk_add_f32 v[102:103], v[70:71], v[102:103]
	v_pk_add_f32 v[100:101], v[68:69], v[100:101]
	v_fmac_f32_e32 v76, v108, v108
	v_fmac_f32_e32 v77, v110, v110
	v_fmac_f32_e32 v72, v104, v104
	v_fmac_f32_e32 v73, v106, v106
	v_mul_f32_e32 v68, v101, v101
	v_mul_f32_e32 v69, v103, v103
	s_waitcnt vmcnt(5)
	v_pk_add_f32 v[98:99], v[66:67], v[98:99]
	v_pk_add_f32 v[96:97], v[64:65], v[96:97]
	v_add_f32_e32 v76, v76, v77
	v_add_f32_e32 v72, v72, v73
	v_fmac_f32_e32 v68, v100, v100
	v_fmac_f32_e32 v69, v102, v102
	v_mul_f32_e32 v64, v97, v97
	v_mul_f32_e32 v65, v99, v99
	v_add_f32_e32 v72, v76, v72
	v_add_f32_e32 v68, v68, v69
	v_fmac_f32_e32 v64, v96, v96
	v_fmac_f32_e32 v65, v98, v98
	v_add_f32_e32 v68, v72, v68
	v_add_f32_e32 v64, v64, v65
	v_add_f32_e32 v64, v68, v64
	ds_bpermute_b32 v65, v189, v64
	s_waitcnt lgkmcnt(0)
	v_add_f32_e32 v64, v64, v65
	ds_bpermute_b32 v65, v191, v64
	s_and_saveexec_b64 s[4:5], vcc
	s_cbranch_execz .LBB0_1330
	s_waitcnt lgkmcnt(0)
	v_add_f32_e32 v64, v64, v65
	global_atomic_add_f32 v190, v[174:175], v64, off offset:192 sc0
	s_nop 0
	s_nop 0
.LBB0_1330:
	s_or_b64 exec, exec, s[4:5]
	v_or_b32_e32 v64, 16, v176
	s_waitcnt lgkmcnt(0)
	v_ashrrev_i32_e32 v65, 31, v64
	v_lshlrev_b64 v[64:65], 13, v[64:65]
	v_lshl_add_u64 v[64:65], s[88:89], 0, v[64:65]
	v_lshl_add_u64 v[64:65], v[144:145], 2, v[64:65]
	global_load_dwordx4 v[76:79], v[64:65], off
	global_load_dwordx4 v[72:75], v[64:65], off offset:64
	global_load_dwordx4 v[68:71], v[64:65], off offset:512
	s_nop 0
	global_load_dwordx4 v[64:67], v[64:65], off offset:576
	s_waitcnt vmcnt(8)
	v_pk_add_f32 v[94:95], v[62:63], v[94:95]
	v_pk_add_f32 v[92:93], v[60:61], v[92:93]
	s_waitcnt vmcnt(7)
	v_pk_add_f32 v[90:91], v[58:59], v[90:91]
	v_pk_add_f32 v[88:89], v[56:57], v[88:89]
	v_mul_f32_e32 v60, v93, v93
	v_mul_f32_e32 v61, v95, v95
	v_mul_f32_e32 v56, v89, v89
	v_mul_f32_e32 v57, v91, v91
	s_waitcnt vmcnt(6)
	v_pk_add_f32 v[86:87], v[54:55], v[86:87]
	v_pk_add_f32 v[84:85], v[52:53], v[84:85]
	v_fmac_f32_e32 v60, v92, v92
	v_fmac_f32_e32 v61, v94, v94
	v_fmac_f32_e32 v56, v88, v88
	v_fmac_f32_e32 v57, v90, v90
	v_mul_f32_e32 v52, v85, v85
	v_mul_f32_e32 v53, v87, v87
	s_waitcnt vmcnt(5)
	v_pk_add_f32 v[82:83], v[50:51], v[82:83]
	v_pk_add_f32 v[80:81], v[48:49], v[80:81]
	v_add_f32_e32 v60, v60, v61
	v_add_f32_e32 v56, v56, v57
	v_fmac_f32_e32 v52, v84, v84
	v_fmac_f32_e32 v53, v86, v86
	v_mul_f32_e32 v48, v81, v81
	v_mul_f32_e32 v49, v83, v83
	v_add_f32_e32 v56, v60, v56
	v_add_f32_e32 v52, v52, v53
	v_fmac_f32_e32 v48, v80, v80
	v_fmac_f32_e32 v49, v82, v82
	v_add_f32_e32 v52, v56, v52
	v_add_f32_e32 v48, v48, v49
	v_add_f32_e32 v48, v52, v48
	ds_bpermute_b32 v49, v189, v48
	v_lshl_add_u64 v[178:179], v[176:177], 2, s[0:1]
	s_waitcnt lgkmcnt(0)
	v_add_f32_e32 v48, v48, v49
	ds_bpermute_b32 v49, v191, v48
	s_and_saveexec_b64 s[0:1], vcc
	s_cbranch_execz .LBB0_1332
	s_waitcnt lgkmcnt(0)
	v_add_f32_e32 v48, v48, v49
	global_atomic_add_f32 v190, v[178:179], v48, off sc0
	s_nop 0
	s_nop 0
; #define EPIDN_LOAD(DST, IDX) do { const float* xr_ = out + (size_t)(row0 + ((IDX) >> 2) * 128 + ((IDX) & 3) * 16) * D + col0; \
;             _Pragma("unroll") for (int bj = 0; bj < 2; ++bj) _Pragma("unroll") for (int n = 0; n < 2; ++n) DST[bj][n] = *(const f32x4*)(xr_ + bj * 128 + n * 16); } while (0)
;     __device__ __forceinline__ void operator()(f32x4 (&acc)[2][2][4][2], const Unit& u, int wr, int wc, int fr, int fq) const {
;     ...
;         for (int idx = 0; idx < 8; ++idx) {
;             const int ai = idx >> 2, m = idx & 3;
;             if (idx + 1 < 8) EPIDN_LOAD(xn, idx + 1);
;             const int row = row0 + ai * 128 + m * 16; float s = 0.f;
; #pragma unroll
;             for (int bj = 0; bj < 2; ++bj)
; #pragma unroll
;                 for (int n = 0; n < 2; ++n) {
;                     const f32x4 x2 = acc[ai][bj][m][n] + xv[bj][n]; acc[ai][bj][m][n] = x2;
;                     s += (x2[0] * x2[0] + x2[1] * x2[1]) + (x2[2] * x2[2] + x2[3] * x2[3]);
;                 }
;             s += __shfl_xor(s, 16); s += __shfl_xor(s, 32);
;             if (fq == 0) chk += unsafeAtomicAdd(rowsq + row, s);
; #pragma unroll
;             for (int bj = 0; bj < 2; ++bj)
; #pragma unroll
;                 for (int n = 0; n < 2; ++n) xv[bj][n] = xn[bj][n];
;         }
.LBB0_1332:
	s_or_b64 exec, exec, s[0:1]
	v_or_b32_e32 v48, 32, v176
	s_waitcnt lgkmcnt(0)
	v_ashrrev_i32_e32 v49, 31, v48
	v_lshlrev_b64 v[48:49], 13, v[48:49]
	v_lshl_add_u64 v[48:49], s[88:89], 0, v[48:49]
	v_lshl_add_u64 v[48:49], v[144:145], 2, v[48:49]
	global_load_dwordx4 v[60:63], v[48:49], off
	global_load_dwordx4 v[56:59], v[48:49], off offset:64
	global_load_dwordx4 v[52:55], v[48:49], off offset:512
	s_nop 0
	global_load_dwordx4 v[48:51], v[48:49], off offset:576
	s_waitcnt vmcnt(8)
	v_pk_add_f32 v[78:79], v[46:47], v[78:79]
	v_pk_add_f32 v[76:77], v[44:45], v[76:77]
	s_waitcnt vmcnt(7)
	v_pk_add_f32 v[74:75], v[42:43], v[74:75]
	v_pk_add_f32 v[72:73], v[40:41], v[72:73]
	v_mul_f32_e32 v44, v77, v77
	v_mul_f32_e32 v45, v79, v79
	v_mul_f32_e32 v40, v73, v73
	v_mul_f32_e32 v41, v75, v75
	s_waitcnt vmcnt(6)
	v_pk_add_f32 v[70:71], v[38:39], v[70:71]
	v_pk_add_f32 v[68:69], v[36:37], v[68:69]
	v_fmac_f32_e32 v44, v76, v76
	v_fmac_f32_e32 v45, v78, v78
	v_fmac_f32_e32 v40, v72, v72
	v_fmac_f32_e32 v41, v74, v74
	v_mul_f32_e32 v36, v69, v69
	v_mul_f32_e32 v37, v71, v71
	s_waitcnt vmcnt(5)
	v_pk_add_f32 v[66:67], v[34:35], v[66:67]
	v_pk_add_f32 v[64:65], v[32:33], v[64:65]
	v_add_f32_e32 v44, v44, v45
	v_add_f32_e32 v40, v40, v41
	v_fmac_f32_e32 v36, v68, v68
	v_fmac_f32_e32 v37, v70, v70
	v_mul_f32_e32 v32, v65, v65
	v_mul_f32_e32 v33, v67, v67
	v_add_f32_e32 v40, v44, v40
	v_add_f32_e32 v36, v36, v37
	v_fmac_f32_e32 v32, v64, v64
	v_fmac_f32_e32 v33, v66, v66
	v_add_f32_e32 v36, v40, v36
	v_add_f32_e32 v32, v32, v33
	v_add_f32_e32 v32, v36, v32
	ds_bpermute_b32 v33, v189, v32
	s_waitcnt lgkmcnt(0)
	v_add_f32_e32 v32, v32, v33
	ds_bpermute_b32 v33, v191, v32
	s_and_saveexec_b64 s[0:1], vcc
	s_cbranch_execz .LBB0_1334
	s_waitcnt lgkmcnt(0)
	v_add_f32_e32 v32, v32, v33
	global_atomic_add_f32 v190, v[178:179], v32, off offset:64 sc0
	s_nop 0
	s_nop 0
.LBB0_1334:
	s_or_b64 exec, exec, s[0:1]
	v_or_b32_e32 v32, 48, v176
	s_waitcnt lgkmcnt(0)
	v_ashrrev_i32_e32 v33, 31, v32
	v_lshlrev_b64 v[32:33], 13, v[32:33]
	v_lshl_add_u64 v[32:33], s[88:89], 0, v[32:33]
	v_lshl_add_u64 v[32:33], v[144:145], 2, v[32:33]
	global_load_dwordx4 v[44:47], v[32:33], off
	global_load_dwordx4 v[40:43], v[32:33], off offset:64
	global_load_dwordx4 v[36:39], v[32:33], off offset:512
	s_nop 0
	global_load_dwordx4 v[32:35], v[32:33], off offset:576
	s_waitcnt vmcnt(8)
	v_pk_add_f32 v[30:31], v[30:31], v[62:63]
	v_pk_add_f32 v[60:61], v[28:29], v[60:61]
	v_mul_f32_e32 v29, v31, v31
	v_mul_f32_e32 v28, v61, v61
	v_fmac_f32_e32 v28, v60, v60
	v_fmac_f32_e32 v29, v30, v30
	s_waitcnt vmcnt(7)
	v_pk_add_f32 v[26:27], v[26:27], v[58:59]
	v_pk_add_f32 v[24:25], v[24:25], v[56:57]
	v_add_f32_e32 v28, v28, v29
	v_mul_f32_e32 v29, v25, v25
	v_mul_f32_e32 v56, v27, v27
	v_fmac_f32_e32 v29, v24, v24
	v_fmac_f32_e32 v56, v26, v26
	v_add_f32_e32 v29, v29, v56
	v_add_f32_e32 v56, v28, v29
	s_waitcnt vmcnt(6)
	v_pk_add_f32 v[22:23], v[22:23], v[54:55]
	v_pk_add_f32 v[28:29], v[20:21], v[52:53]
	v_mul_f32_e32 v21, v23, v23
	v_mul_f32_e32 v20, v29, v29
	v_fmac_f32_e32 v20, v28, v28
	v_fmac_f32_e32 v21, v22, v22
	v_add_f32_e32 v20, v20, v21
	v_add_f32_e32 v52, v56, v20
	s_waitcnt vmcnt(5)
	v_pk_add_f32 v[20:21], v[14:15], v[50:51]
	v_pk_add_f32 v[48:49], v[12:13], v[48:49]
	v_mul_f32_e32 v13, v21, v21
	v_mul_f32_e32 v12, v49, v49
	v_fmac_f32_e32 v12, v48, v48
	v_fmac_f32_e32 v13, v20, v20
	v_add_f32_e32 v12, v12, v13
	v_add_f32_e32 v12, v52, v12
	ds_bpermute_b32 v13, v189, v12
	s_waitcnt lgkmcnt(0)
	v_add_f32_e32 v12, v12, v13
	ds_bpermute_b32 v13, v191, v12
	s_and_saveexec_b64 s[0:1], vcc
	s_cbranch_execz .LBB0_1336
	s_waitcnt lgkmcnt(0)
	v_add_f32_e32 v12, v12, v13
	global_atomic_add_f32 v190, v[178:179], v12, off offset:128 sc0
	s_nop 0
	s_nop 0
.LBB0_1336:
	s_or_b64 exec, exec, s[0:1]
	s_waitcnt vmcnt(4)
	v_pk_add_f32 v[46:47], v[18:19], v[46:47]
	v_pk_add_f32 v[44:45], v[16:17], v[44:45]
	s_waitcnt vmcnt(3)
	v_pk_add_f32 v[16:17], v[10:11], v[42:43]
	v_pk_add_f32 v[40:41], v[8:9], v[40:41]
	v_mul_f32_e32 v12, v45, v45
	s_waitcnt lgkmcnt(0)
	v_mul_f32_e32 v13, v47, v47
	v_mul_f32_e32 v8, v41, v41
	v_mul_f32_e32 v9, v17, v17
	s_waitcnt vmcnt(2)
	v_pk_add_f32 v[18:19], v[6:7], v[38:39]
	v_pk_add_f32 v[36:37], v[4:5], v[36:37]
	v_fmac_f32_e32 v12, v44, v44
	v_fmac_f32_e32 v13, v46, v46
	v_fmac_f32_e32 v8, v40, v40
	v_fmac_f32_e32 v9, v16, v16
	v_mul_f32_e32 v4, v37, v37
	v_mul_f32_e32 v5, v19, v19
	s_waitcnt vmcnt(1)
	v_pk_add_f32 v[34:35], v[2:3], v[34:35]
	v_pk_add_f32 v[32:33], v[0:1], v[32:33]
	v_add_f32_e32 v12, v12, v13
	v_add_f32_e32 v8, v8, v9
	v_fmac_f32_e32 v4, v36, v36
	v_fmac_f32_e32 v5, v18, v18
	v_mul_f32_e32 v0, v33, v33
	v_mul_f32_e32 v1, v35, v35
	v_add_f32_e32 v8, v12, v8
	v_add_f32_e32 v4, v4, v5
	v_fmac_f32_e32 v0, v32, v32
	v_fmac_f32_e32 v1, v34, v34
	v_add_f32_e32 v4, v8, v4
	v_add_f32_e32 v0, v0, v1
	v_add_f32_e32 v0, v4, v0
	ds_bpermute_b32 v1, v189, v0
	s_waitcnt lgkmcnt(0)
	v_add_f32_e32 v0, v0, v1
	ds_bpermute_b32 v1, v191, v0
	s_and_saveexec_b64 s[0:1], vcc
	s_cbranch_execz .LBB0_1338
	s_waitcnt lgkmcnt(0)
	v_add_f32_e32 v0, v0, v1
	global_atomic_add_f32 v190, v[178:179], v0, off offset:192 sc0
	s_nop 0
	s_nop 0
